# static s_setprio 1 for waves 4-7 over the GEMM k-loops, per-block flips deleted (5 loops)
# speedup vs baseline: 1.0116x; 1.0046x over previous
; #define PG8_STAGE(bufoff, gbase, voff) do { _Pragma("unroll") for (int _i = 0; _i < 2; ++_i) \
;         __builtin_amdgcn_global_load_lds((const unsigned*)((const char*)(gbase) + (voff)[_i]), (PG8_LAS unsigned*)(lds + (bufoff) + ldsw + _i * 8192), 16, 0, 0); } while (0)
; #define PG8_LDA(dst, b, h) do { _Pragma("unroll") for (int m = 0; m < 4; ++m) _Pragma("unroll") for (int k = 0; k < 2; ++k) dst[m][k] = *(const PG8_LAS bf16x8*)(lds + PG8_SA(b, h) + aoff + m * 2048 + k * 1024); } while (0)
; #define PG8_LDB(dst, b, h) do { _Pragma("unroll") for (int n = 0; n < 2; ++n) _Pragma("unroll") for (int k = 0; k < 2; ++k) dst[n][k] = *(const PG8_LAS bf16x8*)(lds + PG8_SB(b, h) + boff + n * 2048 + k * 1024); } while (0)
; #define PG8_MMA(ai, bj, At, Bt) do { __builtin_amdgcn_s_setprio(1); _Pragma("unroll") for (int m = 0; m < 4; ++m) _Pragma("unroll") for (int n = 0; n < 2; ++n) _Pragma("unroll") for (int k = 0; k < 2; ++k) \
;         acc[ai][bj][m][n] = __builtin_amdgcn_mfma_f32_16x16x32_bf16(Bt[n][k], At[m][k], acc[ai][bj][m][n], 0, 0, 0); __builtin_amdgcn_s_setprio(0); } while (0)
; #define PG8_WAIT_V(n) asm volatile("s_waitcnt vmcnt(" #n ")" ::: "memory")
; #define PG8_WAIT_L(n) asm volatile("s_waitcnt lgkmcnt(" #n ")" ::: "memory")
; #define PG8_BAR __builtin_amdgcn_s_barrier()
; #define PG8_SCHED __builtin_amdgcn_sched_barrier(0)
; template <class Epi, class Sched, bool ALIGN_EPI = false, bool SP2 = false>
; __device__ __forceinline__ void gemm_phase(PG8_LAS unsigned char* lds, const Gemm g, const Sched& S, const Epi& E) {
;     ...
;             PG8_LDB(B0, 0, 0); PG8_LDB(B1, 0, 1); PG8_SCHED; PG8_LDA(At, 0, 0); PG8_STAGE(PG8_SA(1, 1), a1 + hstepA, voffA);
;             PG8_WAIT_V(8); PG8_WAIT_L(0); PG8_BAR; PG8_MMA(0, 0, At, B0); PG8_MMA(0, 1, At, B1); PG8_BAR; PG8_SCHED;
;     ...
; #pragma unroll
;         for (int a = 0; a < 2; ++a)
; #pragma unroll
;             for (int b = 0; b < 2; ++b)
; #pragma unroll
;                 for (int m = 0; m < 4; ++m)
; #pragma unroll
;                     for (int n = 0; n < 2; ++n) acc[a][b][m][n] = (f32x4){0.f, 0.f, 0.f, 0.f};
.LBB0_364:
	s_ashr_i32 s21, s20, 31
	s_lshl_b64 s[10:11], s[20:21], 21
	s_add_u32 s22, s54, s10
	s_addc_u32 s23, s55, s11
	s_and_b64 s[10:11], s[6:7], exec
	s_cselect_b32 s9, s23, s61
	s_cselect_b32 s10, s22, s60
	s_ashr_i32 s19, s18, 31
	s_lshl_b64 s[24:25], s[18:19], 21
	s_add_u32 s56, s88, s24
	s_addc_u32 s57, s89, s25
	s_and_b64 s[24:25], s[6:7], exec
	s_cselect_b32 s11, s57, s67
	s_cselect_b32 s19, s56, s66
	s_add_u32 s60, s60, 0x100080
	s_addc_u32 s61, s61, 0
	s_add_u32 s21, s66, 0x100
	v_mov_b32_e32 v2, 0
	s_addc_u32 s72, s67, 0
	s_mov_b32 s73, -2
	v_mov_b32_e32 v3, v2
	v_mov_b32_e32 v4, v2
	v_mov_b32_e32 v5, v2
	v_mov_b32_e32 v6, v2
	v_mov_b32_e32 v7, v2
	v_mov_b32_e32 v8, v2
	v_mov_b32_e32 v9, v2
	s_waitcnt vmcnt(0)
	v_mov_b32_e32 v18, v2
	v_mov_b32_e32 v19, v2
	v_mov_b32_e32 v20, v2
	v_mov_b32_e32 v21, v2
	v_mov_b32_e32 v22, v2
	v_mov_b32_e32 v23, v2
	v_mov_b32_e32 v24, v2
	v_mov_b32_e32 v25, v2
	v_mov_b32_e32 v34, v2
	v_mov_b32_e32 v35, v2
	v_mov_b32_e32 v36, v2
	v_mov_b32_e32 v37, v2
	v_mov_b32_e32 v38, v2
	v_mov_b32_e32 v39, v2
	v_mov_b32_e32 v40, v2
	v_mov_b32_e32 v41, v2
	v_mov_b32_e32 v50, v2
	v_mov_b32_e32 v51, v2
	v_mov_b32_e32 v52, v2
	v_mov_b32_e32 v53, v2
	v_mov_b32_e32 v54, v2
	v_mov_b32_e32 v55, v2
	v_mov_b32_e32 v56, v2
	v_mov_b32_e32 v57, v2
	v_mov_b32_e32 v10, v2
	v_mov_b32_e32 v11, v2
	v_mov_b32_e32 v12, v2
	v_mov_b32_e32 v13, v2
	v_mov_b32_e32 v14, v2
	v_mov_b32_e32 v15, v2
	v_mov_b32_e32 v16, v2
	v_mov_b32_e32 v17, v2
	v_mov_b32_e32 v26, v2
	v_mov_b32_e32 v27, v2
	v_mov_b32_e32 v28, v2
	v_mov_b32_e32 v29, v2
	v_mov_b32_e32 v30, v2
	v_mov_b32_e32 v31, v2
	v_mov_b32_e32 v32, v2
	v_mov_b32_e32 v33, v2
	v_mov_b32_e32 v42, v2
	v_mov_b32_e32 v43, v2
	v_mov_b32_e32 v44, v2
	v_mov_b32_e32 v45, v2
	v_mov_b32_e32 v46, v2
	v_mov_b32_e32 v47, v2
	v_mov_b32_e32 v48, v2
	v_mov_b32_e32 v49, v2
	v_mov_b32_e32 v58, v2
	v_mov_b32_e32 v59, v2
	v_mov_b32_e32 v60, v2
	v_mov_b32_e32 v61, v2
	v_mov_b32_e32 v62, v2
	v_mov_b32_e32 v63, v2
	v_mov_b32_e32 v64, v2
	v_mov_b32_e32 v65, v2
	v_mov_b32_e32 v66, v2
	v_mov_b32_e32 v67, v2
	v_mov_b32_e32 v68, v2
	v_mov_b32_e32 v69, v2
	v_mov_b32_e32 v70, v2
	v_mov_b32_e32 v71, v2
	v_mov_b32_e32 v72, v2
	v_mov_b32_e32 v73, v2
	v_mov_b32_e32 v82, v2
	v_mov_b32_e32 v83, v2
	v_mov_b32_e32 v84, v2
	v_mov_b32_e32 v85, v2
	v_mov_b32_e32 v86, v2
	v_mov_b32_e32 v87, v2
	v_mov_b32_e32 v88, v2
	v_mov_b32_e32 v89, v2
	v_mov_b32_e32 v98, v2
	v_mov_b32_e32 v99, v2
	v_mov_b32_e32 v100, v2
	v_mov_b32_e32 v101, v2
	v_mov_b32_e32 v102, v2
	v_mov_b32_e32 v103, v2
	v_mov_b32_e32 v104, v2
	v_mov_b32_e32 v105, v2
	v_mov_b32_e32 v114, v2
	v_mov_b32_e32 v115, v2
	v_mov_b32_e32 v116, v2
	v_mov_b32_e32 v117, v2
	v_mov_b32_e32 v118, v2
	v_mov_b32_e32 v119, v2
	v_mov_b32_e32 v120, v2
	v_mov_b32_e32 v121, v2
	v_mov_b32_e32 v74, v2
	v_mov_b32_e32 v75, v2
	v_mov_b32_e32 v76, v2
	v_mov_b32_e32 v77, v2
	v_mov_b32_e32 v78, v2
	v_mov_b32_e32 v79, v2
	v_mov_b32_e32 v80, v2
	v_mov_b32_e32 v81, v2
	v_mov_b32_e32 v90, v2
	v_mov_b32_e32 v91, v2
	v_mov_b32_e32 v92, v2
	v_mov_b32_e32 v93, v2
	v_mov_b32_e32 v94, v2
	v_mov_b32_e32 v95, v2
	v_mov_b32_e32 v96, v2
	v_mov_b32_e32 v97, v2
	v_mov_b32_e32 v106, v2
	v_mov_b32_e32 v107, v2
	v_mov_b32_e32 v108, v2
	v_mov_b32_e32 v109, v2
	v_mov_b32_e32 v110, v2
	v_mov_b32_e32 v111, v2
	v_mov_b32_e32 v112, v2
	v_mov_b32_e32 v113, v2
	v_mov_b32_e32 v122, v2
	v_mov_b32_e32 v123, v2
	v_mov_b32_e32 v124, v2
	v_mov_b32_e32 v125, v2
	v_mov_b32_e32 v126, v2
	v_mov_b32_e32 v127, v2
	v_mov_b32_e32 v128, v2
	v_mov_b32_e32 v129, v2
	s_setprio 1
	s_cmp_eq_u64 s[16:17], 0
	s_cbranch_scc1 .Lsp_LBB0_365
	s_setprio 0
.Lsp_LBB0_365:
.LBB0_365:
	ds_read_b128 v[154:157], v169
	ds_read_b128 v[158:161], v169 offset:1024
	ds_read_b128 v[162:165], v169 offset:2048
	ds_read_b128 v[174:177], v169 offset:3072
	ds_read_b128 v[178:181], v170
	ds_read_b128 v[182:185], v170 offset:1024
	ds_read_b128 v[186:189], v170 offset:2048
	ds_read_b128 v[190:193], v170 offset:3072
	s_add_u32 s24, s60, 0xfff00080
	s_addc_u32 s25, s61, -1
	s_cmp_eq_u32 s73, 60
	s_cselect_b32 s25, s9, s25
	s_cselect_b32 s24, s10, s24
	s_cselect_b32 s67, s11, s72
	s_cselect_b32 s66, s19, s21
	s_add_i32 m0, s27, 0xc000
	ds_read_b128 v[194:197], v171
	ds_read_b128 v[198:201], v171 offset:1024
	ds_read_b128 v[202:205], v171 offset:2048
	ds_read_b128 v[206:209], v171 offset:3072
	ds_read_b128 v[210:213], v171 offset:4096
	ds_read_b128 v[214:217], v171 offset:5120
	ds_read_b128 v[218:221], v171 offset:6144
	ds_read_b128 v[222:225], v171 offset:7168
	global_load_lds_dwordx4 v146, s[60:61]
	s_add_i32 m0, s27, 0xe000
	s_nop 0
	global_load_lds_dwordx4 v148, s[60:61]
	s_waitcnt vmcnt(8)
	s_waitcnt lgkmcnt(0)
	s_barrier
; #define PG8_STAGE(bufoff, gbase, voff) do { _Pragma("unroll") for (int _i = 0; _i < 2; ++_i) \
;         __builtin_amdgcn_global_load_lds((const unsigned*)((const char*)(gbase) + (voff)[_i]), (PG8_LAS unsigned*)(lds + (bufoff) + ldsw + _i * 8192), 16, 0, 0); } while (0)
; #define PG8_LDA(dst, b, h) do { _Pragma("unroll") for (int m = 0; m < 4; ++m) _Pragma("unroll") for (int k = 0; k < 2; ++k) dst[m][k] = *(const PG8_LAS bf16x8*)(lds + PG8_SA(b, h) + aoff + m * 2048 + k * 1024); } while (0)
; #define PG8_MMA(ai, bj, At, Bt) do { __builtin_amdgcn_s_setprio(1); _Pragma("unroll") for (int m = 0; m < 4; ++m) _Pragma("unroll") for (int n = 0; n < 2; ++n) _Pragma("unroll") for (int k = 0; k < 2; ++k) \
;         acc[ai][bj][m][n] = __builtin_amdgcn_mfma_f32_16x16x32_bf16(Bt[n][k], At[m][k], acc[ai][bj][m][n], 0, 0, 0); __builtin_amdgcn_s_setprio(0); } while (0)
; #define PG8_WAIT_V(n) asm volatile("s_waitcnt vmcnt(" #n ")" ::: "memory")
; #define PG8_WAIT_L(n) asm volatile("s_waitcnt lgkmcnt(" #n ")" ::: "memory")
; #define PG8_BAR __builtin_amdgcn_s_barrier()
; #define PG8_SCHED __builtin_amdgcn_sched_barrier(0)
; template <class Epi, class Sched, bool ALIGN_EPI = false, bool SP2 = false>
; __device__ __forceinline__ void gemm_phase(PG8_LAS unsigned char* lds, const Gemm g, const Sched& S, const Epi& E) {
;     ...
;             PG8_WAIT_V(8); PG8_WAIT_L(0); PG8_BAR; PG8_MMA(0, 0, At, B0); PG8_MMA(0, 1, At, B1); PG8_BAR; PG8_SCHED;
;             PG8_LDA(At, 0, 1); PG8_STAGE(PG8_SB(0, 0), b2, voffB); PG8_STAGE(PG8_SB(0, 1), b2 + hstepB, voffB); PG8_STAGE(PG8_SA(0, 0), a2, voffA);
;             PG8_WAIT_V(8); PG8_WAIT_L(0); PG8_BAR; PG8_MMA(1, 0, At, B0); PG8_MMA(1, 1, At, B1); PG8_BAR; PG8_SCHED;
	s_waitcnt lgkmcnt(0)
	v_mfma_f32_16x16x32_bf16 v[126:129], v[154:157], v[194:197], v[126:129]
	v_mfma_f32_16x16x32_bf16 v[122:125], v[162:165], v[194:197], v[122:125]
	v_mfma_f32_16x16x32_bf16 v[110:113], v[154:157], v[202:205], v[110:113]
	v_mfma_f32_16x16x32_bf16 v[106:109], v[162:165], v[202:205], v[106:109]
	v_mfma_f32_16x16x32_bf16 v[94:97], v[154:157], v[210:213], v[94:97]
	v_mfma_f32_16x16x32_bf16 v[90:93], v[162:165], v[210:213], v[90:93]
	v_mfma_f32_16x16x32_bf16 v[78:81], v[154:157], v[218:221], v[78:81]
	v_mfma_f32_16x16x32_bf16 v[74:77], v[162:165], v[218:221], v[74:77]
	v_mfma_f32_16x16x32_bf16 v[126:129], v[158:161], v[198:201], v[126:129]
	v_mfma_f32_16x16x32_bf16 v[122:125], v[174:177], v[198:201], v[122:125]
	v_mfma_f32_16x16x32_bf16 v[110:113], v[158:161], v[206:209], v[110:113]
	v_mfma_f32_16x16x32_bf16 v[106:109], v[174:177], v[206:209], v[106:109]
	v_mfma_f32_16x16x32_bf16 v[94:97], v[158:161], v[214:217], v[94:97]
	v_mfma_f32_16x16x32_bf16 v[90:93], v[174:177], v[214:217], v[90:93]
	v_mfma_f32_16x16x32_bf16 v[78:81], v[158:161], v[222:225], v[78:81]
	v_mfma_f32_16x16x32_bf16 v[74:77], v[174:177], v[222:225], v[74:77]
	v_mfma_f32_16x16x32_bf16 v[118:121], v[178:181], v[194:197], v[118:121]
	v_mfma_f32_16x16x32_bf16 v[114:117], v[186:189], v[194:197], v[114:117]
	v_mfma_f32_16x16x32_bf16 v[102:105], v[178:181], v[202:205], v[102:105]
	v_mfma_f32_16x16x32_bf16 v[98:101], v[186:189], v[202:205], v[98:101]
	v_mfma_f32_16x16x32_bf16 v[86:89], v[178:181], v[210:213], v[86:89]
	v_mfma_f32_16x16x32_bf16 v[82:85], v[186:189], v[210:213], v[82:85]
	v_mfma_f32_16x16x32_bf16 v[70:73], v[178:181], v[218:221], v[70:73]
	v_mfma_f32_16x16x32_bf16 v[66:69], v[186:189], v[218:221], v[66:69]
	v_mfma_f32_16x16x32_bf16 v[118:121], v[182:185], v[198:201], v[118:121]
	v_mfma_f32_16x16x32_bf16 v[114:117], v[190:193], v[198:201], v[114:117]
	v_mfma_f32_16x16x32_bf16 v[102:105], v[182:185], v[206:209], v[102:105]
	v_mfma_f32_16x16x32_bf16 v[98:101], v[190:193], v[206:209], v[98:101]
	v_mfma_f32_16x16x32_bf16 v[86:89], v[182:185], v[214:217], v[86:89]
	v_mfma_f32_16x16x32_bf16 v[82:85], v[190:193], v[214:217], v[82:85]
	v_mfma_f32_16x16x32_bf16 v[70:73], v[182:185], v[222:225], v[70:73]
	v_mfma_f32_16x16x32_bf16 v[66:69], v[190:193], v[222:225], v[66:69]
	s_barrier
	s_add_i32 s74, s47, s26
	s_add_u32 s98, s66, 0x80
	s_addc_u32 s99, s67, 0
	s_add_u32 s100, s24, 0x80
	s_addc_u32 s101, s25, 0
	s_mov_b32 m0, s74
	ds_read_b128 v[194:197], v171 offset:16384
	ds_read_b128 v[198:201], v171 offset:17408
	ds_read_b128 v[202:205], v171 offset:18432
	ds_read_b128 v[206:209], v171 offset:19456
	ds_read_b128 v[210:213], v171 offset:20480
	ds_read_b128 v[214:217], v171 offset:21504
	ds_read_b128 v[218:221], v171 offset:22528
	ds_read_b128 v[222:225], v171 offset:23552
	global_load_lds_dwordx4 v132, s[66:67]
	s_add_i32 m0, s74, 0x2000
	s_add_u32 s74, s66, 0x100000
	s_addc_u32 s75, s67, 0
	s_add_i32 s76, s48, s26
	global_load_lds_dwordx4 v136, s[66:67]
	s_mov_b32 m0, s76
	s_nop 0
	global_load_lds_dwordx4 v132, s[74:75]
	s_add_i32 m0, s76, 0x2000
	s_nop 0
	global_load_lds_dwordx4 v136, s[74:75]
	s_mov_b32 m0, s27
	s_nop 0
	global_load_lds_dwordx4 v130, s[24:25]
	s_mov_b32 m0, s34
	s_nop 0
	global_load_lds_dwordx4 v134, s[24:25]
	s_waitcnt vmcnt(8)
	s_waitcnt lgkmcnt(0)
	s_barrier
	s_waitcnt lgkmcnt(0)
	v_mfma_f32_16x16x32_bf16 v[62:65], v[154:157], v[194:197], v[62:65]
	v_mfma_f32_16x16x32_bf16 v[58:61], v[162:165], v[194:197], v[58:61]
	v_mfma_f32_16x16x32_bf16 v[46:49], v[154:157], v[202:205], v[46:49]
	v_mfma_f32_16x16x32_bf16 v[42:45], v[162:165], v[202:205], v[42:45]
	v_mfma_f32_16x16x32_bf16 v[30:33], v[154:157], v[210:213], v[30:33]
	v_mfma_f32_16x16x32_bf16 v[26:29], v[162:165], v[210:213], v[26:29]
	v_mfma_f32_16x16x32_bf16 v[14:17], v[154:157], v[218:221], v[14:17]
	v_mfma_f32_16x16x32_bf16 v[10:13], v[162:165], v[218:221], v[10:13]
	v_mfma_f32_16x16x32_bf16 v[62:65], v[158:161], v[198:201], v[62:65]
	v_mfma_f32_16x16x32_bf16 v[58:61], v[174:177], v[198:201], v[58:61]
	v_mfma_f32_16x16x32_bf16 v[46:49], v[158:161], v[206:209], v[46:49]
	v_mfma_f32_16x16x32_bf16 v[42:45], v[174:177], v[206:209], v[42:45]
	v_mfma_f32_16x16x32_bf16 v[30:33], v[158:161], v[214:217], v[30:33]
	v_mfma_f32_16x16x32_bf16 v[26:29], v[174:177], v[214:217], v[26:29]
	v_mfma_f32_16x16x32_bf16 v[14:17], v[158:161], v[222:225], v[14:17]
	v_mfma_f32_16x16x32_bf16 v[10:13], v[174:177], v[222:225], v[10:13]
	v_mfma_f32_16x16x32_bf16 v[54:57], v[178:181], v[194:197], v[54:57]
	v_mfma_f32_16x16x32_bf16 v[50:53], v[186:189], v[194:197], v[50:53]
	v_mfma_f32_16x16x32_bf16 v[38:41], v[178:181], v[202:205], v[38:41]
	v_mfma_f32_16x16x32_bf16 v[34:37], v[186:189], v[202:205], v[34:37]
	v_mfma_f32_16x16x32_bf16 v[22:25], v[178:181], v[210:213], v[22:25]
	v_mfma_f32_16x16x32_bf16 v[18:21], v[186:189], v[210:213], v[18:21]
	v_mfma_f32_16x16x32_bf16 v[6:9], v[178:181], v[218:221], v[6:9]
	v_mfma_f32_16x16x32_bf16 v[2:5], v[186:189], v[218:221], v[2:5]
	v_mfma_f32_16x16x32_bf16 v[54:57], v[182:185], v[198:201], v[54:57]
	v_mfma_f32_16x16x32_bf16 v[50:53], v[190:193], v[198:201], v[50:53]
	v_mfma_f32_16x16x32_bf16 v[38:41], v[182:185], v[206:209], v[38:41]
	v_mfma_f32_16x16x32_bf16 v[34:37], v[190:193], v[206:209], v[34:37]
	v_mfma_f32_16x16x32_bf16 v[22:25], v[182:185], v[214:217], v[22:25]
	v_mfma_f32_16x16x32_bf16 v[18:21], v[190:193], v[214:217], v[18:21]
	v_mfma_f32_16x16x32_bf16 v[6:9], v[182:185], v[222:225], v[6:9]
	v_mfma_f32_16x16x32_bf16 v[2:5], v[190:193], v[222:225], v[2:5]
	s_barrier
; #define PG8_STAGE(bufoff, gbase, voff) do { _Pragma("unroll") for (int _i = 0; _i < 2; ++_i) \
;         __builtin_amdgcn_global_load_lds((const unsigned*)((const char*)(gbase) + (voff)[_i]), (PG8_LAS unsigned*)(lds + (bufoff) + ldsw + _i * 8192), 16, 0, 0); } while (0)
; #define PG8_LDA(dst, b, h) do { _Pragma("unroll") for (int m = 0; m < 4; ++m) _Pragma("unroll") for (int k = 0; k < 2; ++k) dst[m][k] = *(const PG8_LAS bf16x8*)(lds + PG8_SA(b, h) + aoff + m * 2048 + k * 1024); } while (0)
; #define PG8_LDB(dst, b, h) do { _Pragma("unroll") for (int n = 0; n < 2; ++n) _Pragma("unroll") for (int k = 0; k < 2; ++k) dst[n][k] = *(const PG8_LAS bf16x8*)(lds + PG8_SB(b, h) + boff + n * 2048 + k * 1024); } while (0)
; #define PG8_MMA(ai, bj, At, Bt) do { __builtin_amdgcn_s_setprio(1); _Pragma("unroll") for (int m = 0; m < 4; ++m) _Pragma("unroll") for (int n = 0; n < 2; ++n) _Pragma("unroll") for (int k = 0; k < 2; ++k) \
;         acc[ai][bj][m][n] = __builtin_amdgcn_mfma_f32_16x16x32_bf16(Bt[n][k], At[m][k], acc[ai][bj][m][n], 0, 0, 0); __builtin_amdgcn_s_setprio(0); } while (0)
; #define PG8_WAIT_V(n) asm volatile("s_waitcnt vmcnt(" #n ")" ::: "memory")
; #define PG8_WAIT_L(n) asm volatile("s_waitcnt lgkmcnt(" #n ")" ::: "memory")
; #define PG8_BAR __builtin_amdgcn_s_barrier()
; #define PG8_SCHED __builtin_amdgcn_sched_barrier(0)
; template <class Epi, class Sched, bool ALIGN_EPI = false, bool SP2 = false>
; __device__ __forceinline__ void gemm_phase(PG8_LAS unsigned char* lds, const Gemm g, const Sched& S, const Epi& E) {
;     ...
;         for (int t = 0; t < nt; t += 2) {
;     ...
;             PG8_LDB(B0, 1, 0); PG8_LDB(B1, 1, 1); PG8_SCHED; PG8_LDA(At, 1, 0); PG8_STAGE(PG8_SA(0, 1), a2 + hstepA, voffA);
;             PG8_WAIT_V(8); PG8_WAIT_L(0); PG8_BAR; PG8_MMA(0, 0, At, B0); PG8_MMA(0, 1, At, B1); PG8_BAR; PG8_SCHED;
;             PG8_LDA(At, 1, 1); PG8_STAGE(PG8_SB(1, 0), b3, voffB); PG8_STAGE(PG8_SB(1, 1), b3 + hstepB, voffB); PG8_STAGE(PG8_SA(1, 0), a3, voffA);
;             PG8_WAIT_V(8); PG8_WAIT_L(0); PG8_BAR; PG8_MMA(1, 0, At, B0); PG8_MMA(1, 1, At, B1); PG8_BAR; PG8_SCHED;
	s_add_i32 s74, 0, 0x18000
	v_add_u32_e32 v138, s74, v141
	s_add_i32 s75, 0, 0x1c000
	ds_read_b128 v[154:157], v138
	ds_read_b128 v[158:161], v138 offset:1024
	ds_read_b128 v[162:165], v138 offset:2048
	ds_read_b128 v[174:177], v138 offset:3072
	v_add_u32_e32 v138, s75, v141
	ds_read_b128 v[178:181], v138
	ds_read_b128 v[182:185], v138 offset:1024
	ds_read_b128 v[186:189], v138 offset:2048
	ds_read_b128 v[190:193], v138 offset:3072
	s_add_u32 s24, s24, 0x100000
	s_addc_u32 s25, s25, 0
	s_mov_b32 m0, s35
	ds_read_b128 v[194:197], v171 offset:32768
	ds_read_b128 v[198:201], v171 offset:33792
	ds_read_b128 v[202:205], v171 offset:34816
	ds_read_b128 v[206:209], v171 offset:35840
	ds_read_b128 v[210:213], v171 offset:36864
	ds_read_b128 v[214:217], v171 offset:37888
	ds_read_b128 v[218:221], v171 offset:38912
	ds_read_b128 v[222:225], v171 offset:39936
	global_load_lds_dwordx4 v130, s[24:25]
	s_mov_b32 m0, s36
	s_nop 0
	global_load_lds_dwordx4 v134, s[24:25]
	s_waitcnt vmcnt(8)
	s_waitcnt lgkmcnt(0)
	s_barrier
	s_waitcnt lgkmcnt(0)
	v_mfma_f32_16x16x32_bf16 v[126:129], v[154:157], v[194:197], v[126:129]
	v_mfma_f32_16x16x32_bf16 v[122:125], v[162:165], v[194:197], v[122:125]
	v_mfma_f32_16x16x32_bf16 v[110:113], v[154:157], v[202:205], v[110:113]
	v_mfma_f32_16x16x32_bf16 v[106:109], v[162:165], v[202:205], v[106:109]
	v_mfma_f32_16x16x32_bf16 v[94:97], v[154:157], v[210:213], v[94:97]
	v_mfma_f32_16x16x32_bf16 v[90:93], v[162:165], v[210:213], v[90:93]
	v_mfma_f32_16x16x32_bf16 v[78:81], v[154:157], v[218:221], v[78:81]
	v_mfma_f32_16x16x32_bf16 v[74:77], v[162:165], v[218:221], v[74:77]
	v_mfma_f32_16x16x32_bf16 v[126:129], v[158:161], v[198:201], v[126:129]
	v_mfma_f32_16x16x32_bf16 v[122:125], v[174:177], v[198:201], v[122:125]
	v_mfma_f32_16x16x32_bf16 v[110:113], v[158:161], v[206:209], v[110:113]
	v_mfma_f32_16x16x32_bf16 v[106:109], v[174:177], v[206:209], v[106:109]
	v_mfma_f32_16x16x32_bf16 v[94:97], v[158:161], v[214:217], v[94:97]
	v_mfma_f32_16x16x32_bf16 v[90:93], v[174:177], v[214:217], v[90:93]
	v_mfma_f32_16x16x32_bf16 v[78:81], v[158:161], v[222:225], v[78:81]
	v_mfma_f32_16x16x32_bf16 v[74:77], v[174:177], v[222:225], v[74:77]
	v_mfma_f32_16x16x32_bf16 v[118:121], v[178:181], v[194:197], v[118:121]
	v_mfma_f32_16x16x32_bf16 v[114:117], v[186:189], v[194:197], v[114:117]
	v_mfma_f32_16x16x32_bf16 v[102:105], v[178:181], v[202:205], v[102:105]
	v_mfma_f32_16x16x32_bf16 v[98:101], v[186:189], v[202:205], v[98:101]
	v_mfma_f32_16x16x32_bf16 v[86:89], v[178:181], v[210:213], v[86:89]
	v_mfma_f32_16x16x32_bf16 v[82:85], v[186:189], v[210:213], v[82:85]
	v_mfma_f32_16x16x32_bf16 v[70:73], v[178:181], v[218:221], v[70:73]
	v_mfma_f32_16x16x32_bf16 v[66:69], v[186:189], v[218:221], v[66:69]
	v_mfma_f32_16x16x32_bf16 v[118:121], v[182:185], v[198:201], v[118:121]
	v_mfma_f32_16x16x32_bf16 v[114:117], v[190:193], v[198:201], v[114:117]
	v_mfma_f32_16x16x32_bf16 v[102:105], v[182:185], v[206:209], v[102:105]
	v_mfma_f32_16x16x32_bf16 v[98:101], v[190:193], v[206:209], v[98:101]
	v_mfma_f32_16x16x32_bf16 v[86:89], v[182:185], v[214:217], v[86:89]
	v_mfma_f32_16x16x32_bf16 v[82:85], v[190:193], v[214:217], v[82:85]
	v_mfma_f32_16x16x32_bf16 v[70:73], v[182:185], v[222:225], v[70:73]
	v_mfma_f32_16x16x32_bf16 v[66:69], v[190:193], v[222:225], v[66:69]
	s_barrier
	s_add_i32 s24, s74, s26
	s_mov_b32 m0, s24
	ds_read_b128 v[194:197], v171 offset:49152
	ds_read_b128 v[198:201], v171 offset:50176
	ds_read_b128 v[202:205], v171 offset:51200
	ds_read_b128 v[206:209], v171 offset:52224
	ds_read_b128 v[210:213], v171 offset:53248
	ds_read_b128 v[214:217], v171 offset:54272
	ds_read_b128 v[218:221], v171 offset:55296
	ds_read_b128 v[222:225], v171 offset:56320
	global_load_lds_dwordx4 v132, s[98:99]
	s_add_i32 m0, s24, 0x2000
	s_add_u32 s24, s66, 0x100080
	s_addc_u32 s25, s67, 0
	s_add_i32 s66, s75, s26
	global_load_lds_dwordx4 v136, s[98:99]
	s_mov_b32 m0, s66
	s_nop 0
	global_load_lds_dwordx4 v132, s[24:25]
	s_add_i32 m0, s66, 0x2000
	s_nop 0
	global_load_lds_dwordx4 v136, s[24:25]
	s_mov_b32 m0, s42
	s_nop 0
	global_load_lds_dwordx4 v130, s[100:101]
	s_mov_b32 m0, s43
	s_nop 0
	global_load_lds_dwordx4 v134, s[100:101]
	s_waitcnt vmcnt(8)
	s_waitcnt lgkmcnt(0)
	s_barrier
	s_waitcnt lgkmcnt(0)
	v_mfma_f32_16x16x32_bf16 v[62:65], v[154:157], v[194:197], v[62:65]
	v_mfma_f32_16x16x32_bf16 v[58:61], v[162:165], v[194:197], v[58:61]
	v_mfma_f32_16x16x32_bf16 v[46:49], v[154:157], v[202:205], v[46:49]
	v_mfma_f32_16x16x32_bf16 v[42:45], v[162:165], v[202:205], v[42:45]
	v_mfma_f32_16x16x32_bf16 v[30:33], v[154:157], v[210:213], v[30:33]
	v_mfma_f32_16x16x32_bf16 v[26:29], v[162:165], v[210:213], v[26:29]
	v_mfma_f32_16x16x32_bf16 v[14:17], v[154:157], v[218:221], v[14:17]
	v_mfma_f32_16x16x32_bf16 v[10:13], v[162:165], v[218:221], v[10:13]
	v_mfma_f32_16x16x32_bf16 v[62:65], v[158:161], v[198:201], v[62:65]
	v_mfma_f32_16x16x32_bf16 v[58:61], v[174:177], v[198:201], v[58:61]
	v_mfma_f32_16x16x32_bf16 v[46:49], v[158:161], v[206:209], v[46:49]
	v_mfma_f32_16x16x32_bf16 v[42:45], v[174:177], v[206:209], v[42:45]
	v_mfma_f32_16x16x32_bf16 v[30:33], v[158:161], v[214:217], v[30:33]
	v_mfma_f32_16x16x32_bf16 v[26:29], v[174:177], v[214:217], v[26:29]
	v_mfma_f32_16x16x32_bf16 v[14:17], v[158:161], v[222:225], v[14:17]
	v_mfma_f32_16x16x32_bf16 v[10:13], v[174:177], v[222:225], v[10:13]
	v_mfma_f32_16x16x32_bf16 v[54:57], v[178:181], v[194:197], v[54:57]
	v_mfma_f32_16x16x32_bf16 v[50:53], v[186:189], v[194:197], v[50:53]
	v_mfma_f32_16x16x32_bf16 v[38:41], v[178:181], v[202:205], v[38:41]
	v_mfma_f32_16x16x32_bf16 v[34:37], v[186:189], v[202:205], v[34:37]
	v_mfma_f32_16x16x32_bf16 v[22:25], v[178:181], v[210:213], v[22:25]
	v_mfma_f32_16x16x32_bf16 v[18:21], v[186:189], v[210:213], v[18:21]
	v_mfma_f32_16x16x32_bf16 v[6:9], v[178:181], v[218:221], v[6:9]
	v_mfma_f32_16x16x32_bf16 v[2:5], v[186:189], v[218:221], v[2:5]
	v_mfma_f32_16x16x32_bf16 v[54:57], v[182:185], v[198:201], v[54:57]
	v_mfma_f32_16x16x32_bf16 v[50:53], v[190:193], v[198:201], v[50:53]
	v_mfma_f32_16x16x32_bf16 v[38:41], v[182:185], v[206:209], v[38:41]
	v_mfma_f32_16x16x32_bf16 v[34:37], v[190:193], v[206:209], v[34:37]
	v_mfma_f32_16x16x32_bf16 v[22:25], v[182:185], v[214:217], v[22:25]
	v_mfma_f32_16x16x32_bf16 v[18:21], v[190:193], v[214:217], v[18:21]
	v_mfma_f32_16x16x32_bf16 v[6:9], v[182:185], v[222:225], v[6:9]
	v_mfma_f32_16x16x32_bf16 v[2:5], v[190:193], v[222:225], v[2:5]
	s_barrier
	s_add_i32 s73, s73, 2
	s_add_u32 s60, s60, 0x100
	s_addc_u32 s61, s61, 0
	s_add_u32 s21, s21, 0x100
	s_addc_u32 s72, s72, 0
	s_cmp_gt_u32 s73, 61
	s_cbranch_scc0 .LBB0_365
	s_setprio 0
	s_and_b64 vcc, exec, s[16:17]
	s_cbranch_vccz .LBB0_368
	s_barrier

; #define PG8_STAGE(bufoff, gbase, voff) do { _Pragma("unroll") for (int _i = 0; _i < 2; ++_i) \
;         __builtin_amdgcn_global_load_lds((const unsigned*)((const char*)(gbase) + (voff)[_i]), (PG8_LAS unsigned*)(lds + (bufoff) + ldsw + _i * 8192), 16, 0, 0); } while (0)
; #define PG8_LDA(dst, b, h) do { _Pragma("unroll") for (int m = 0; m < 4; ++m) _Pragma("unroll") for (int k = 0; k < 2; ++k) dst[m][k] = *(const PG8_LAS bf16x8*)(lds + PG8_SA(b, h) + aoff + m * 2048 + k * 1024); } while (0)
; #define PG8_LDB(dst, b, h) do { _Pragma("unroll") for (int n = 0; n < 2; ++n) _Pragma("unroll") for (int k = 0; k < 2; ++k) dst[n][k] = *(const PG8_LAS bf16x8*)(lds + PG8_SB(b, h) + boff + n * 2048 + k * 1024); } while (0)
; #define PG8_MMA(ai, bj, At, Bt) do { __builtin_amdgcn_s_setprio(1); _Pragma("unroll") for (int m = 0; m < 4; ++m) _Pragma("unroll") for (int n = 0; n < 2; ++n) _Pragma("unroll") for (int k = 0; k < 2; ++k) \
;         acc[ai][bj][m][n] = __builtin_amdgcn_mfma_f32_16x16x32_bf16(Bt[n][k], At[m][k], acc[ai][bj][m][n], 0, 0, 0); __builtin_amdgcn_s_setprio(0); } while (0)
; #define PG8_WAIT_V(n) asm volatile("s_waitcnt vmcnt(" #n ")" ::: "memory")
; #define PG8_WAIT_L(n) asm volatile("s_waitcnt lgkmcnt(" #n ")" ::: "memory")
; #define PG8_BAR __builtin_amdgcn_s_barrier()
; #define PG8_SCHED __builtin_amdgcn_sched_barrier(0)
; template <class Epi, class Sched, bool ALIGN_EPI = false, bool SP2 = false>
; __device__ __forceinline__ void gemm_phase(PG8_LAS unsigned char* lds, const Gemm g, const Sched& S, const Epi& E) {
;     ...
;             PG8_LDB(B0, 0, 0); PG8_LDB(B1, 0, 1); PG8_SCHED; PG8_LDA(At, 0, 0); PG8_STAGE(PG8_SA(1, 1), a1 + hstepA, voffA);
;             PG8_WAIT_V(8); PG8_WAIT_L(0); PG8_BAR; PG8_MMA(0, 0, At, B0); PG8_MMA(0, 1, At, B1); PG8_BAR; PG8_SCHED;
;     ...
; #pragma unroll
;         for (int a = 0; a < 2; ++a)
; #pragma unroll
;             for (int b = 0; b < 2; ++b)
; #pragma unroll
;                 for (int m = 0; m < 4; ++m)
; #pragma unroll
;                     for (int n = 0; n < 2; ++n) acc[a][b][m][n] = (f32x4){0.f, 0.f, 0.f, 0.f};
.LBB0_838:
	s_ashr_i32 s17, s16, 31
	s_lshl_b64 s[18:19], s[16:17], 21
	s_add_u32 s18, s31, s18
	s_addc_u32 s19, s58, s19
	s_and_b64 s[20:21], s[4:5], exec
	s_cselect_b32 s17, s19, s37
	s_cselect_b32 s49, s18, s36
	s_ashr_i32 s15, s14, 31
	s_lshl_b64 s[20:21], s[14:15], 21
	v_readlane_b32 s24, v254, 38
	v_readlane_b32 s25, v254, 39
	s_add_u32 s20, s24, s20
	s_addc_u32 s21, s25, s21
	s_and_b64 s[24:25], s[4:5], exec
	s_cselect_b32 s15, s21, s39
	s_cselect_b32 s62, s20, s38
	s_add_u32 s36, s36, 0x100080
	s_addc_u32 s37, s37, 0
	s_add_u32 s63, s38, 0x100
	v_mov_b32_e32 v2, 0
	s_addc_u32 s68, s39, 0
	s_mov_b32 s69, -2
	v_mov_b32_e32 v3, v2
	v_mov_b32_e32 v4, v2
	v_mov_b32_e32 v5, v2
	v_mov_b32_e32 v6, v2
	v_mov_b32_e32 v7, v2
	v_mov_b32_e32 v8, v2
	v_mov_b32_e32 v9, v2
	v_mov_b32_e32 v14, v2
	v_mov_b32_e32 v15, v2
	v_mov_b32_e32 v16, v2
	v_mov_b32_e32 v17, v2
	v_mov_b32_e32 v22, v2
	v_mov_b32_e32 v23, v2
	v_mov_b32_e32 v24, v2
	v_mov_b32_e32 v25, v2
	v_mov_b32_e32 v30, v2
	v_mov_b32_e32 v31, v2
	v_mov_b32_e32 v32, v2
	v_mov_b32_e32 v33, v2
	v_mov_b32_e32 v38, v2
	v_mov_b32_e32 v39, v2
	v_mov_b32_e32 v40, v2
	v_mov_b32_e32 v41, v2
	v_mov_b32_e32 v46, v2
	v_mov_b32_e32 v47, v2
	v_mov_b32_e32 v48, v2
	v_mov_b32_e32 v49, v2
	v_mov_b32_e32 v54, v2
	v_mov_b32_e32 v55, v2
	v_mov_b32_e32 v56, v2
	v_mov_b32_e32 v57, v2
	v_mov_b32_e32 v10, v2
	v_mov_b32_e32 v11, v2
	v_mov_b32_e32 v12, v2
	v_mov_b32_e32 v13, v2
	v_mov_b32_e32 v18, v2
	v_mov_b32_e32 v19, v2
	v_mov_b32_e32 v20, v2
	v_mov_b32_e32 v21, v2
	v_mov_b32_e32 v26, v2
	v_mov_b32_e32 v27, v2
	v_mov_b32_e32 v28, v2
	v_mov_b32_e32 v29, v2
	v_mov_b32_e32 v34, v2
	v_mov_b32_e32 v35, v2
	v_mov_b32_e32 v36, v2
	v_mov_b32_e32 v37, v2
	v_mov_b32_e32 v42, v2
	v_mov_b32_e32 v43, v2
	v_mov_b32_e32 v44, v2
	v_mov_b32_e32 v45, v2
	v_mov_b32_e32 v50, v2
	v_mov_b32_e32 v51, v2
	v_mov_b32_e32 v52, v2
	v_mov_b32_e32 v53, v2
	v_mov_b32_e32 v58, v2
	v_mov_b32_e32 v59, v2
	v_mov_b32_e32 v60, v2
	v_mov_b32_e32 v61, v2
	v_mov_b32_e32 v62, v2
	v_mov_b32_e32 v63, v2
	v_mov_b32_e32 v64, v2
	v_mov_b32_e32 v65, v2
	v_mov_b32_e32 v66, v2
	v_mov_b32_e32 v67, v2
	v_mov_b32_e32 v68, v2
	v_mov_b32_e32 v69, v2
	v_mov_b32_e32 v70, v2
	v_mov_b32_e32 v71, v2
	v_mov_b32_e32 v72, v2
	v_mov_b32_e32 v73, v2
	v_mov_b32_e32 v74, v2
	v_mov_b32_e32 v75, v2
	v_mov_b32_e32 v76, v2
	v_mov_b32_e32 v77, v2
	v_mov_b32_e32 v78, v2
	v_mov_b32_e32 v79, v2
	v_mov_b32_e32 v80, v2
	v_mov_b32_e32 v81, v2
	v_mov_b32_e32 v82, v2
	v_mov_b32_e32 v83, v2
	v_mov_b32_e32 v84, v2
	v_mov_b32_e32 v85, v2
	v_mov_b32_e32 v90, v2
	v_mov_b32_e32 v91, v2
	v_mov_b32_e32 v92, v2
	v_mov_b32_e32 v93, v2
	v_mov_b32_e32 v98, v2
	v_mov_b32_e32 v99, v2
	v_mov_b32_e32 v100, v2
	v_mov_b32_e32 v101, v2
	v_mov_b32_e32 v106, v2
	v_mov_b32_e32 v107, v2
	v_mov_b32_e32 v108, v2
	v_mov_b32_e32 v109, v2
	v_mov_b32_e32 v86, v2
	v_mov_b32_e32 v87, v2
	v_mov_b32_e32 v88, v2
	v_mov_b32_e32 v89, v2
	v_mov_b32_e32 v94, v2
	v_mov_b32_e32 v95, v2
	v_mov_b32_e32 v96, v2
	v_mov_b32_e32 v97, v2
	v_mov_b32_e32 v102, v2
	v_mov_b32_e32 v103, v2
	v_mov_b32_e32 v104, v2
	v_mov_b32_e32 v105, v2
	v_mov_b32_e32 v110, v2
	v_mov_b32_e32 v111, v2
	v_mov_b32_e32 v112, v2
	v_mov_b32_e32 v113, v2
	v_mov_b32_e32 v114, v2
	v_mov_b32_e32 v115, v2
	v_mov_b32_e32 v116, v2
	v_mov_b32_e32 v117, v2
	v_mov_b32_e32 v118, v2
	v_mov_b32_e32 v119, v2
	v_mov_b32_e32 v120, v2
	v_mov_b32_e32 v121, v2
	v_mov_b32_e32 v122, v2
	v_mov_b32_e32 v123, v2
	v_mov_b32_e32 v124, v2
	v_mov_b32_e32 v125, v2
	v_mov_b32_e32 v126, v2
	v_mov_b32_e32 v127, v2
	v_mov_b32_e32 v128, v2
	v_mov_b32_e32 v129, v2
	s_setprio 1
	s_cmp_eq_u64 s[10:11], 0
	s_cbranch_scc1 .Lsp_LBB0_839
	s_setprio 0
.Lsp_LBB0_839:
.LBB0_839:
	ds_read_b128 v[130:133], v166
	ds_read_b128 v[134:137], v166 offset:1024
	ds_read_b128 v[138:141], v166 offset:2048
	ds_read_b128 v[142:145], v166 offset:3072
	ds_read_b128 v[170:173], v167
	ds_read_b128 v[174:177], v167 offset:1024
	ds_read_b128 v[178:181], v167 offset:2048
	ds_read_b128 v[182:185], v167 offset:3072
	s_add_u32 s24, s36, 0xfff00080
	s_addc_u32 s25, s37, -1
	s_cmp_eq_u32 s69, 60
	s_cselect_b32 s25, s17, s25
	s_cselect_b32 s24, s49, s24
	s_cselect_b32 s39, s15, s68
	s_cselect_b32 s38, s62, s63
	s_add_i32 m0, s23, 0xc000
	ds_read_b128 v[186:189], v168
	ds_read_b128 v[190:193], v168 offset:1024
	ds_read_b128 v[194:197], v168 offset:2048
	ds_read_b128 v[198:201], v168 offset:3072
	ds_read_b128 v[202:205], v168 offset:4096
	ds_read_b128 v[206:209], v168 offset:5120
	ds_read_b128 v[210:213], v168 offset:6144
	ds_read_b128 v[214:217], v168 offset:7168
	global_load_lds_dwordx4 v154, s[36:37]
	s_add_i32 m0, s23, 0xe000
	s_nop 0
	global_load_lds_dwordx4 v156, s[36:37]
	s_waitcnt vmcnt(8)
	s_waitcnt lgkmcnt(0)
	s_barrier
; #define PG8_STAGE(bufoff, gbase, voff) do { _Pragma("unroll") for (int _i = 0; _i < 2; ++_i) \
;         __builtin_amdgcn_global_load_lds((const unsigned*)((const char*)(gbase) + (voff)[_i]), (PG8_LAS unsigned*)(lds + (bufoff) + ldsw + _i * 8192), 16, 0, 0); } while (0)
; #define PG8_LDA(dst, b, h) do { _Pragma("unroll") for (int m = 0; m < 4; ++m) _Pragma("unroll") for (int k = 0; k < 2; ++k) dst[m][k] = *(const PG8_LAS bf16x8*)(lds + PG8_SA(b, h) + aoff + m * 2048 + k * 1024); } while (0)
; #define PG8_MMA(ai, bj, At, Bt) do { __builtin_amdgcn_s_setprio(1); _Pragma("unroll") for (int m = 0; m < 4; ++m) _Pragma("unroll") for (int n = 0; n < 2; ++n) _Pragma("unroll") for (int k = 0; k < 2; ++k) \
;         acc[ai][bj][m][n] = __builtin_amdgcn_mfma_f32_16x16x32_bf16(Bt[n][k], At[m][k], acc[ai][bj][m][n], 0, 0, 0); __builtin_amdgcn_s_setprio(0); } while (0)
; #define PG8_WAIT_V(n) asm volatile("s_waitcnt vmcnt(" #n ")" ::: "memory")
; #define PG8_WAIT_L(n) asm volatile("s_waitcnt lgkmcnt(" #n ")" ::: "memory")
; #define PG8_BAR __builtin_amdgcn_s_barrier()
; #define PG8_SCHED __builtin_amdgcn_sched_barrier(0)
; template <class Epi, class Sched, bool ALIGN_EPI = false, bool SP2 = false>
; __device__ __forceinline__ void gemm_phase(PG8_LAS unsigned char* lds, const Gemm g, const Sched& S, const Epi& E) {
;     ...
;             PG8_WAIT_V(8); PG8_WAIT_L(0); PG8_BAR; PG8_MMA(0, 0, At, B0); PG8_MMA(0, 1, At, B1); PG8_BAR; PG8_SCHED;
;             PG8_LDA(At, 0, 1); PG8_STAGE(PG8_SB(0, 0), b2, voffB); PG8_STAGE(PG8_SB(0, 1), b2 + hstepB, voffB); PG8_STAGE(PG8_SA(0, 0), a2, voffA);
;             PG8_WAIT_V(8); PG8_WAIT_L(0); PG8_BAR; PG8_MMA(1, 0, At, B0); PG8_MMA(1, 1, At, B1); PG8_BAR; PG8_SCHED;
	s_waitcnt lgkmcnt(0)
	v_mfma_f32_16x16x32_bf16 v[126:129], v[130:133], v[186:189], v[126:129]
	v_mfma_f32_16x16x32_bf16 v[122:125], v[138:141], v[186:189], v[122:125]
	v_mfma_f32_16x16x32_bf16 v[118:121], v[130:133], v[194:197], v[118:121]
	v_mfma_f32_16x16x32_bf16 v[114:117], v[138:141], v[194:197], v[114:117]
	v_mfma_f32_16x16x32_bf16 v[110:113], v[130:133], v[202:205], v[110:113]
	v_mfma_f32_16x16x32_bf16 v[102:105], v[138:141], v[202:205], v[102:105]
	v_mfma_f32_16x16x32_bf16 v[94:97], v[130:133], v[210:213], v[94:97]
	v_mfma_f32_16x16x32_bf16 v[86:89], v[138:141], v[210:213], v[86:89]
	v_mfma_f32_16x16x32_bf16 v[126:129], v[134:137], v[190:193], v[126:129]
	v_mfma_f32_16x16x32_bf16 v[122:125], v[142:145], v[190:193], v[122:125]
	v_mfma_f32_16x16x32_bf16 v[118:121], v[134:137], v[198:201], v[118:121]
	v_mfma_f32_16x16x32_bf16 v[114:117], v[142:145], v[198:201], v[114:117]
	v_mfma_f32_16x16x32_bf16 v[110:113], v[134:137], v[206:209], v[110:113]
	v_mfma_f32_16x16x32_bf16 v[102:105], v[142:145], v[206:209], v[102:105]
	v_mfma_f32_16x16x32_bf16 v[94:97], v[134:137], v[214:217], v[94:97]
	v_mfma_f32_16x16x32_bf16 v[86:89], v[142:145], v[214:217], v[86:89]
	v_mfma_f32_16x16x32_bf16 v[106:109], v[170:173], v[186:189], v[106:109]
	v_mfma_f32_16x16x32_bf16 v[98:101], v[178:181], v[186:189], v[98:101]
	v_mfma_f32_16x16x32_bf16 v[90:93], v[170:173], v[194:197], v[90:93]
	v_mfma_f32_16x16x32_bf16 v[82:85], v[178:181], v[194:197], v[82:85]
	v_mfma_f32_16x16x32_bf16 v[78:81], v[170:173], v[202:205], v[78:81]
	v_mfma_f32_16x16x32_bf16 v[74:77], v[178:181], v[202:205], v[74:77]
	v_mfma_f32_16x16x32_bf16 v[70:73], v[170:173], v[210:213], v[70:73]
	v_mfma_f32_16x16x32_bf16 v[66:69], v[178:181], v[210:213], v[66:69]
	v_mfma_f32_16x16x32_bf16 v[106:109], v[174:177], v[190:193], v[106:109]
	v_mfma_f32_16x16x32_bf16 v[98:101], v[182:185], v[190:193], v[98:101]
	v_mfma_f32_16x16x32_bf16 v[90:93], v[174:177], v[198:201], v[90:93]
	v_mfma_f32_16x16x32_bf16 v[82:85], v[182:185], v[198:201], v[82:85]
	v_mfma_f32_16x16x32_bf16 v[78:81], v[174:177], v[206:209], v[78:81]
	v_mfma_f32_16x16x32_bf16 v[74:77], v[182:185], v[206:209], v[74:77]
	v_mfma_f32_16x16x32_bf16 v[70:73], v[174:177], v[214:217], v[70:73]
	v_mfma_f32_16x16x32_bf16 v[66:69], v[182:185], v[214:217], v[66:69]
	s_barrier
	s_add_i32 s72, s45, s26
	s_add_u32 s98, s38, 0x80
	s_addc_u32 s99, s39, 0
	s_add_u32 s100, s24, 0x80
	s_addc_u32 s101, s25, 0
	s_mov_b32 m0, s72
	ds_read_b128 v[186:189], v168 offset:16384
	ds_read_b128 v[190:193], v168 offset:17408
	ds_read_b128 v[194:197], v168 offset:18432
	ds_read_b128 v[198:201], v168 offset:19456
	ds_read_b128 v[202:205], v168 offset:20480
	ds_read_b128 v[206:209], v168 offset:21504
	ds_read_b128 v[210:213], v168 offset:22528
	ds_read_b128 v[214:217], v168 offset:23552
	global_load_lds_dwordx4 v150, s[38:39]
	s_add_i32 m0, s72, 0x2000
	s_add_u32 s72, s38, 0x100000
	s_addc_u32 s73, s39, 0
	s_add_i32 s74, s46, s26
	global_load_lds_dwordx4 v146, s[38:39]
	s_mov_b32 m0, s74
	s_nop 0
	global_load_lds_dwordx4 v150, s[72:73]
	s_add_i32 m0, s74, 0x2000
	s_nop 0
	global_load_lds_dwordx4 v146, s[72:73]
	s_mov_b32 m0, s23
	s_nop 0
	global_load_lds_dwordx4 v152, s[24:25]
	s_mov_b32 m0, s27
	s_nop 0
	global_load_lds_dwordx4 v148, s[24:25]
	s_waitcnt vmcnt(8)
	s_waitcnt lgkmcnt(0)
	s_barrier
	s_waitcnt lgkmcnt(0)
	v_mfma_f32_16x16x32_bf16 v[62:65], v[130:133], v[186:189], v[62:65]
	v_mfma_f32_16x16x32_bf16 v[58:61], v[138:141], v[186:189], v[58:61]
	v_mfma_f32_16x16x32_bf16 v[50:53], v[130:133], v[194:197], v[50:53]
	v_mfma_f32_16x16x32_bf16 v[42:45], v[138:141], v[194:197], v[42:45]
	v_mfma_f32_16x16x32_bf16 v[34:37], v[130:133], v[202:205], v[34:37]
	v_mfma_f32_16x16x32_bf16 v[26:29], v[138:141], v[202:205], v[26:29]
	v_mfma_f32_16x16x32_bf16 v[18:21], v[130:133], v[210:213], v[18:21]
	v_mfma_f32_16x16x32_bf16 v[10:13], v[138:141], v[210:213], v[10:13]
	v_mfma_f32_16x16x32_bf16 v[62:65], v[134:137], v[190:193], v[62:65]
	v_mfma_f32_16x16x32_bf16 v[58:61], v[142:145], v[190:193], v[58:61]
	v_mfma_f32_16x16x32_bf16 v[50:53], v[134:137], v[198:201], v[50:53]
	v_mfma_f32_16x16x32_bf16 v[42:45], v[142:145], v[198:201], v[42:45]
	v_mfma_f32_16x16x32_bf16 v[34:37], v[134:137], v[206:209], v[34:37]
	v_mfma_f32_16x16x32_bf16 v[26:29], v[142:145], v[206:209], v[26:29]
	v_mfma_f32_16x16x32_bf16 v[18:21], v[134:137], v[214:217], v[18:21]
	v_mfma_f32_16x16x32_bf16 v[10:13], v[142:145], v[214:217], v[10:13]
	v_mfma_f32_16x16x32_bf16 v[54:57], v[170:173], v[186:189], v[54:57]
	v_mfma_f32_16x16x32_bf16 v[46:49], v[178:181], v[186:189], v[46:49]
	v_mfma_f32_16x16x32_bf16 v[38:41], v[170:173], v[194:197], v[38:41]
	v_mfma_f32_16x16x32_bf16 v[30:33], v[178:181], v[194:197], v[30:33]
	v_mfma_f32_16x16x32_bf16 v[22:25], v[170:173], v[202:205], v[22:25]
	v_mfma_f32_16x16x32_bf16 v[14:17], v[178:181], v[202:205], v[14:17]
	v_mfma_f32_16x16x32_bf16 v[6:9], v[170:173], v[210:213], v[6:9]
	v_mfma_f32_16x16x32_bf16 v[2:5], v[178:181], v[210:213], v[2:5]
	v_mfma_f32_16x16x32_bf16 v[54:57], v[174:177], v[190:193], v[54:57]
	v_mfma_f32_16x16x32_bf16 v[46:49], v[182:185], v[190:193], v[46:49]
	v_mfma_f32_16x16x32_bf16 v[38:41], v[174:177], v[198:201], v[38:41]
	v_mfma_f32_16x16x32_bf16 v[30:33], v[182:185], v[198:201], v[30:33]
	v_mfma_f32_16x16x32_bf16 v[22:25], v[174:177], v[206:209], v[22:25]
	v_mfma_f32_16x16x32_bf16 v[14:17], v[182:185], v[206:209], v[14:17]
	v_mfma_f32_16x16x32_bf16 v[6:9], v[174:177], v[214:217], v[6:9]
	v_mfma_f32_16x16x32_bf16 v[2:5], v[182:185], v[214:217], v[2:5]
	s_barrier
; #define PG8_STAGE(bufoff, gbase, voff) do { _Pragma("unroll") for (int _i = 0; _i < 2; ++_i) \
;         __builtin_amdgcn_global_load_lds((const unsigned*)((const char*)(gbase) + (voff)[_i]), (PG8_LAS unsigned*)(lds + (bufoff) + ldsw + _i * 8192), 16, 0, 0); } while (0)
; #define PG8_LDA(dst, b, h) do { _Pragma("unroll") for (int m = 0; m < 4; ++m) _Pragma("unroll") for (int k = 0; k < 2; ++k) dst[m][k] = *(const PG8_LAS bf16x8*)(lds + PG8_SA(b, h) + aoff + m * 2048 + k * 1024); } while (0)
; #define PG8_LDB(dst, b, h) do { _Pragma("unroll") for (int n = 0; n < 2; ++n) _Pragma("unroll") for (int k = 0; k < 2; ++k) dst[n][k] = *(const PG8_LAS bf16x8*)(lds + PG8_SB(b, h) + boff + n * 2048 + k * 1024); } while (0)
; #define PG8_MMA(ai, bj, At, Bt) do { __builtin_amdgcn_s_setprio(1); _Pragma("unroll") for (int m = 0; m < 4; ++m) _Pragma("unroll") for (int n = 0; n < 2; ++n) _Pragma("unroll") for (int k = 0; k < 2; ++k) \
;         acc[ai][bj][m][n] = __builtin_amdgcn_mfma_f32_16x16x32_bf16(Bt[n][k], At[m][k], acc[ai][bj][m][n], 0, 0, 0); __builtin_amdgcn_s_setprio(0); } while (0)
; #define PG8_WAIT_V(n) asm volatile("s_waitcnt vmcnt(" #n ")" ::: "memory")
; #define PG8_WAIT_L(n) asm volatile("s_waitcnt lgkmcnt(" #n ")" ::: "memory")
; #define PG8_BAR __builtin_amdgcn_s_barrier()
; #define PG8_SCHED __builtin_amdgcn_sched_barrier(0)
; template <class Epi, class Sched, bool ALIGN_EPI = false, bool SP2 = false>
; __device__ __forceinline__ void gemm_phase(PG8_LAS unsigned char* lds, const Gemm g, const Sched& S, const Epi& E) {
;     ...
;         for (int t = 0; t < nt; t += 2) {
;     ...
;             PG8_LDB(B0, 1, 0); PG8_LDB(B1, 1, 1); PG8_SCHED; PG8_LDA(At, 1, 0); PG8_STAGE(PG8_SA(0, 1), a2 + hstepA, voffA);
;             PG8_WAIT_V(8); PG8_WAIT_L(0); PG8_BAR; PG8_MMA(0, 0, At, B0); PG8_MMA(0, 1, At, B1); PG8_BAR; PG8_SCHED;
;             PG8_LDA(At, 1, 1); PG8_STAGE(PG8_SB(1, 0), b3, voffB); PG8_STAGE(PG8_SB(1, 1), b3 + hstepB, voffB); PG8_STAGE(PG8_SA(1, 0), a3, voffA);
;             PG8_WAIT_V(8); PG8_WAIT_L(0); PG8_BAR; PG8_MMA(1, 0, At, B0); PG8_MMA(1, 1, At, B1); PG8_BAR; PG8_SCHED;
	s_add_i32 s72, 0, 0x18000
	s_add_i32 s73, 0, 0x1c000
	v_add_u32_e32 v142, s72, v164
	v_add_u32_e32 v169, s73, v164
	ds_read_b128 v[130:133], v142
	ds_read_b128 v[134:137], v142 offset:1024
	ds_read_b128 v[138:141], v142 offset:2048
	ds_read_b128 v[142:145], v142 offset:3072
	ds_read_b128 v[170:173], v169
	ds_read_b128 v[174:177], v169 offset:1024
	ds_read_b128 v[178:181], v169 offset:2048
	ds_read_b128 v[182:185], v169 offset:3072
	s_add_u32 s24, s24, 0x100000
	s_addc_u32 s25, s25, 0
	s_mov_b32 m0, s34
	ds_read_b128 v[186:189], v168 offset:32768
	ds_read_b128 v[190:193], v168 offset:33792
	ds_read_b128 v[194:197], v168 offset:34816
	ds_read_b128 v[198:201], v168 offset:35840
	ds_read_b128 v[202:205], v168 offset:36864
	ds_read_b128 v[206:209], v168 offset:37888
	ds_read_b128 v[210:213], v168 offset:38912
	ds_read_b128 v[214:217], v168 offset:39936
	global_load_lds_dwordx4 v152, s[24:25]
	s_mov_b32 m0, s35
	s_nop 0
	global_load_lds_dwordx4 v148, s[24:25]
	s_waitcnt vmcnt(8)
	s_waitcnt lgkmcnt(0)
	s_barrier
	s_waitcnt lgkmcnt(0)
	v_mfma_f32_16x16x32_bf16 v[126:129], v[130:133], v[186:189], v[126:129]
	v_mfma_f32_16x16x32_bf16 v[122:125], v[138:141], v[186:189], v[122:125]
	v_mfma_f32_16x16x32_bf16 v[118:121], v[130:133], v[194:197], v[118:121]
	v_mfma_f32_16x16x32_bf16 v[114:117], v[138:141], v[194:197], v[114:117]
	v_mfma_f32_16x16x32_bf16 v[110:113], v[130:133], v[202:205], v[110:113]
	v_mfma_f32_16x16x32_bf16 v[102:105], v[138:141], v[202:205], v[102:105]
	v_mfma_f32_16x16x32_bf16 v[94:97], v[130:133], v[210:213], v[94:97]
	v_mfma_f32_16x16x32_bf16 v[86:89], v[138:141], v[210:213], v[86:89]
	v_mfma_f32_16x16x32_bf16 v[126:129], v[134:137], v[190:193], v[126:129]
	v_mfma_f32_16x16x32_bf16 v[122:125], v[142:145], v[190:193], v[122:125]
	v_mfma_f32_16x16x32_bf16 v[118:121], v[134:137], v[198:201], v[118:121]
	v_mfma_f32_16x16x32_bf16 v[114:117], v[142:145], v[198:201], v[114:117]
	v_mfma_f32_16x16x32_bf16 v[110:113], v[134:137], v[206:209], v[110:113]
	v_mfma_f32_16x16x32_bf16 v[102:105], v[142:145], v[206:209], v[102:105]
	v_mfma_f32_16x16x32_bf16 v[94:97], v[134:137], v[214:217], v[94:97]
	v_mfma_f32_16x16x32_bf16 v[86:89], v[142:145], v[214:217], v[86:89]
	v_mfma_f32_16x16x32_bf16 v[106:109], v[170:173], v[186:189], v[106:109]
	v_mfma_f32_16x16x32_bf16 v[98:101], v[178:181], v[186:189], v[98:101]
	v_mfma_f32_16x16x32_bf16 v[90:93], v[170:173], v[194:197], v[90:93]
	v_mfma_f32_16x16x32_bf16 v[82:85], v[178:181], v[194:197], v[82:85]
	v_mfma_f32_16x16x32_bf16 v[78:81], v[170:173], v[202:205], v[78:81]
	v_mfma_f32_16x16x32_bf16 v[74:77], v[178:181], v[202:205], v[74:77]
	v_mfma_f32_16x16x32_bf16 v[70:73], v[170:173], v[210:213], v[70:73]
	v_mfma_f32_16x16x32_bf16 v[66:69], v[178:181], v[210:213], v[66:69]
	v_mfma_f32_16x16x32_bf16 v[106:109], v[174:177], v[190:193], v[106:109]
	v_mfma_f32_16x16x32_bf16 v[98:101], v[182:185], v[190:193], v[98:101]
	v_mfma_f32_16x16x32_bf16 v[90:93], v[174:177], v[198:201], v[90:93]
	v_mfma_f32_16x16x32_bf16 v[82:85], v[182:185], v[198:201], v[82:85]
	v_mfma_f32_16x16x32_bf16 v[78:81], v[174:177], v[206:209], v[78:81]
	v_mfma_f32_16x16x32_bf16 v[74:77], v[182:185], v[206:209], v[74:77]
	v_mfma_f32_16x16x32_bf16 v[70:73], v[174:177], v[214:217], v[70:73]
	v_mfma_f32_16x16x32_bf16 v[66:69], v[182:185], v[214:217], v[66:69]
	s_barrier
	s_add_i32 s24, s72, s26
	s_mov_b32 m0, s24
	ds_read_b128 v[186:189], v168 offset:49152
	ds_read_b128 v[190:193], v168 offset:50176
	ds_read_b128 v[194:197], v168 offset:51200
	ds_read_b128 v[198:201], v168 offset:52224
	ds_read_b128 v[202:205], v168 offset:53248
	ds_read_b128 v[206:209], v168 offset:54272
	ds_read_b128 v[210:213], v168 offset:55296
	ds_read_b128 v[214:217], v168 offset:56320
	global_load_lds_dwordx4 v150, s[98:99]
	s_add_i32 m0, s24, 0x2000
	s_add_u32 s24, s38, 0x100080
	s_addc_u32 s25, s39, 0
	s_add_i32 s38, s73, s26
	global_load_lds_dwordx4 v146, s[98:99]
	s_mov_b32 m0, s38
	s_nop 0
	global_load_lds_dwordx4 v150, s[24:25]
	s_add_i32 m0, s38, 0x2000
	s_nop 0
	global_load_lds_dwordx4 v146, s[24:25]
	s_mov_b32 m0, s43
	s_nop 0
	global_load_lds_dwordx4 v152, s[100:101]
	s_mov_b32 m0, s44
	s_nop 0
	global_load_lds_dwordx4 v148, s[100:101]
	s_waitcnt vmcnt(8)
	s_waitcnt lgkmcnt(0)
	s_barrier
	s_waitcnt lgkmcnt(0)
	v_mfma_f32_16x16x32_bf16 v[62:65], v[130:133], v[186:189], v[62:65]
	v_mfma_f32_16x16x32_bf16 v[58:61], v[138:141], v[186:189], v[58:61]
	v_mfma_f32_16x16x32_bf16 v[50:53], v[130:133], v[194:197], v[50:53]
	v_mfma_f32_16x16x32_bf16 v[42:45], v[138:141], v[194:197], v[42:45]
	v_mfma_f32_16x16x32_bf16 v[34:37], v[130:133], v[202:205], v[34:37]
	v_mfma_f32_16x16x32_bf16 v[26:29], v[138:141], v[202:205], v[26:29]
	v_mfma_f32_16x16x32_bf16 v[18:21], v[130:133], v[210:213], v[18:21]
	v_mfma_f32_16x16x32_bf16 v[10:13], v[138:141], v[210:213], v[10:13]
	v_mfma_f32_16x16x32_bf16 v[62:65], v[134:137], v[190:193], v[62:65]
	v_mfma_f32_16x16x32_bf16 v[58:61], v[142:145], v[190:193], v[58:61]
	v_mfma_f32_16x16x32_bf16 v[50:53], v[134:137], v[198:201], v[50:53]
	v_mfma_f32_16x16x32_bf16 v[42:45], v[142:145], v[198:201], v[42:45]
	v_mfma_f32_16x16x32_bf16 v[34:37], v[134:137], v[206:209], v[34:37]
	v_mfma_f32_16x16x32_bf16 v[26:29], v[142:145], v[206:209], v[26:29]
	v_mfma_f32_16x16x32_bf16 v[18:21], v[134:137], v[214:217], v[18:21]
	v_mfma_f32_16x16x32_bf16 v[10:13], v[142:145], v[214:217], v[10:13]
	v_mfma_f32_16x16x32_bf16 v[54:57], v[170:173], v[186:189], v[54:57]
	v_mfma_f32_16x16x32_bf16 v[46:49], v[178:181], v[186:189], v[46:49]
	v_mfma_f32_16x16x32_bf16 v[38:41], v[170:173], v[194:197], v[38:41]
	v_mfma_f32_16x16x32_bf16 v[30:33], v[178:181], v[194:197], v[30:33]
	v_mfma_f32_16x16x32_bf16 v[22:25], v[170:173], v[202:205], v[22:25]
	v_mfma_f32_16x16x32_bf16 v[14:17], v[178:181], v[202:205], v[14:17]
	v_mfma_f32_16x16x32_bf16 v[6:9], v[170:173], v[210:213], v[6:9]
	v_mfma_f32_16x16x32_bf16 v[2:5], v[178:181], v[210:213], v[2:5]
	v_mfma_f32_16x16x32_bf16 v[54:57], v[174:177], v[190:193], v[54:57]
	v_mfma_f32_16x16x32_bf16 v[46:49], v[182:185], v[190:193], v[46:49]
	v_mfma_f32_16x16x32_bf16 v[38:41], v[174:177], v[198:201], v[38:41]
	v_mfma_f32_16x16x32_bf16 v[30:33], v[182:185], v[198:201], v[30:33]
	v_mfma_f32_16x16x32_bf16 v[22:25], v[174:177], v[206:209], v[22:25]
	v_mfma_f32_16x16x32_bf16 v[14:17], v[182:185], v[206:209], v[14:17]
	v_mfma_f32_16x16x32_bf16 v[6:9], v[174:177], v[214:217], v[6:9]
	v_mfma_f32_16x16x32_bf16 v[2:5], v[182:185], v[214:217], v[2:5]
	s_barrier
	s_add_i32 s69, s69, 2
	s_add_u32 s36, s36, 0x100
	s_addc_u32 s37, s37, 0
	s_add_u32 s63, s63, 0x100
	s_addc_u32 s68, s68, 0
	s_cmp_gt_u32 s69, 61
	s_cbranch_scc0 .LBB0_839
	s_setprio 0
	s_and_b64 vcc, exec, s[10:11]
	s_cbranch_vccz .LBB0_842
	s_barrier

; #define PG8_STAGE(bufoff, gbase, voff) do { _Pragma("unroll") for (int _i = 0; _i < 2; ++_i) \
;         __builtin_amdgcn_global_load_lds((const unsigned*)((const char*)(gbase) + (voff)[_i]), (PG8_LAS unsigned*)(lds + (bufoff) + ldsw + _i * 8192), 16, 0, 0); } while (0)
; #define PG8_LDA(dst, b, h) do { _Pragma("unroll") for (int m = 0; m < 4; ++m) _Pragma("unroll") for (int k = 0; k < 2; ++k) dst[m][k] = *(const PG8_LAS bf16x8*)(lds + PG8_SA(b, h) + aoff + m * 2048 + k * 1024); } while (0)
; #define PG8_LDB(dst, b, h) do { _Pragma("unroll") for (int n = 0; n < 2; ++n) _Pragma("unroll") for (int k = 0; k < 2; ++k) dst[n][k] = *(const PG8_LAS bf16x8*)(lds + PG8_SB(b, h) + boff + n * 2048 + k * 1024); } while (0)
; #define PG8_MMA(ai, bj, At, Bt) do { __builtin_amdgcn_s_setprio(1); _Pragma("unroll") for (int m = 0; m < 4; ++m) _Pragma("unroll") for (int n = 0; n < 2; ++n) _Pragma("unroll") for (int k = 0; k < 2; ++k) \
;         acc[ai][bj][m][n] = __builtin_amdgcn_mfma_f32_16x16x32_bf16(Bt[n][k], At[m][k], acc[ai][bj][m][n], 0, 0, 0); __builtin_amdgcn_s_setprio(0); } while (0)
; #define PG8_WAIT_V(n) asm volatile("s_waitcnt vmcnt(" #n ")" ::: "memory")
; #define PG8_WAIT_L(n) asm volatile("s_waitcnt lgkmcnt(" #n ")" ::: "memory")
; #define PG8_BAR __builtin_amdgcn_s_barrier()
; #define PG8_SCHED __builtin_amdgcn_sched_barrier(0)
; template <class Epi, class Sched, bool ALIGN_EPI = false, bool SP2 = false>
; __device__ __forceinline__ void gemm_phase(PG8_LAS unsigned char* lds, const Gemm g, const Sched& S, const Epi& E) {
;     ...
;             PG8_LDB(B0, 0, 0); PG8_LDB(B1, 0, 1); PG8_SCHED; PG8_LDA(At, 0, 0); PG8_STAGE(PG8_SA(1, 1), a1 + hstepA, voffA);
;             PG8_WAIT_V(8); PG8_WAIT_L(0); PG8_BAR; PG8_MMA(0, 0, At, B0); PG8_MMA(0, 1, At, B1); PG8_BAR; PG8_SCHED;
;     ...
; #pragma unroll
;         for (int a = 0; a < 2; ++a)
; #pragma unroll
;             for (int b = 0; b < 2; ++b)
; #pragma unroll
;                 for (int m = 0; m < 4; ++m)
; #pragma unroll
;                     for (int n = 0; n < 2; ++n) acc[a][b][m][n] = (f32x4){0.f, 0.f, 0.f, 0.f};
.LBB0_989:
	s_ashr_i32 s23, s22, 31
	s_lshl_b64 s[24:25], s[22:23], 21
	s_add_u32 s24, s92, s24
	s_addc_u32 s25, s93, s25
	s_and_b64 s[34:35], s[6:7], exec
	s_cselect_b32 s23, s25, s41
	s_cselect_b32 s27, s24, s40
	s_ashr_i32 s21, s20, 31
	s_lshl_b64 s[34:35], s[20:21], 21
	s_add_u32 s36, s54, s34
	s_addc_u32 s37, s55, s35
	s_and_b64 s[34:35], s[6:7], exec
	s_cselect_b32 s21, s37, s43
	s_cselect_b32 s39, s36, s42
	s_add_u32 s40, s40, 0x100080
	s_addc_u32 s41, s41, 0
	s_add_u32 s72, s42, 0x100
	v_mov_b32_e32 v2, 0
	s_addc_u32 s73, s43, 0
	s_mov_b32 s74, -2
	v_mov_b32_e32 v3, v2
	v_mov_b32_e32 v4, v2
	v_mov_b32_e32 v5, v2
	v_mov_b32_e32 v6, v2
	v_mov_b32_e32 v7, v2
	v_mov_b32_e32 v8, v2
	v_mov_b32_e32 v9, v2
	v_mov_b32_e32 v10, v2
	v_mov_b32_e32 v11, v2
	v_mov_b32_e32 v12, v2
	v_mov_b32_e32 v13, v2
	v_mov_b32_e32 v14, v2
	v_mov_b32_e32 v15, v2
	v_mov_b32_e32 v16, v2
	v_mov_b32_e32 v17, v2
	v_mov_b32_e32 v18, v2
	v_mov_b32_e32 v19, v2
	v_mov_b32_e32 v20, v2
	v_mov_b32_e32 v21, v2
	v_mov_b32_e32 v22, v2
	v_mov_b32_e32 v23, v2
	v_mov_b32_e32 v24, v2
	v_mov_b32_e32 v25, v2
	v_mov_b32_e32 v26, v2
	v_mov_b32_e32 v27, v2
	v_mov_b32_e32 v28, v2
	v_mov_b32_e32 v29, v2
	v_mov_b32_e32 v30, v2
	v_mov_b32_e32 v31, v2
	v_mov_b32_e32 v32, v2
	v_mov_b32_e32 v33, v2
	v_mov_b32_e32 v66, v2
	v_mov_b32_e32 v67, v2
	v_mov_b32_e32 v68, v2
	v_mov_b32_e32 v69, v2
	v_mov_b32_e32 v70, v2
	v_mov_b32_e32 v71, v2
	v_mov_b32_e32 v72, v2
	v_mov_b32_e32 v73, v2
	v_mov_b32_e32 v74, v2
	v_mov_b32_e32 v75, v2
	v_mov_b32_e32 v76, v2
	v_mov_b32_e32 v77, v2
	v_mov_b32_e32 v78, v2
	v_mov_b32_e32 v79, v2
	v_mov_b32_e32 v80, v2
	v_mov_b32_e32 v81, v2
	v_mov_b32_e32 v82, v2
	v_mov_b32_e32 v83, v2
	v_mov_b32_e32 v84, v2
	v_mov_b32_e32 v85, v2
	v_mov_b32_e32 v86, v2
	v_mov_b32_e32 v87, v2
	v_mov_b32_e32 v88, v2
	v_mov_b32_e32 v89, v2
	v_mov_b32_e32 v90, v2
	v_mov_b32_e32 v91, v2
	v_mov_b32_e32 v92, v2
	v_mov_b32_e32 v93, v2
	v_mov_b32_e32 v94, v2
	v_mov_b32_e32 v95, v2
	v_mov_b32_e32 v96, v2
	v_mov_b32_e32 v97, v2
	v_mov_b32_e32 v34, v2
	v_mov_b32_e32 v35, v2
	v_mov_b32_e32 v36, v2
	v_mov_b32_e32 v37, v2
	v_mov_b32_e32 v38, v2
	v_mov_b32_e32 v39, v2
	v_mov_b32_e32 v40, v2
	v_mov_b32_e32 v41, v2
	v_mov_b32_e32 v42, v2
	v_mov_b32_e32 v43, v2
	v_mov_b32_e32 v44, v2
	v_mov_b32_e32 v45, v2
	v_mov_b32_e32 v46, v2
	v_mov_b32_e32 v47, v2
	v_mov_b32_e32 v48, v2
	v_mov_b32_e32 v49, v2
	v_mov_b32_e32 v50, v2
	v_mov_b32_e32 v51, v2
	v_mov_b32_e32 v52, v2
	v_mov_b32_e32 v53, v2
	v_mov_b32_e32 v54, v2
	v_mov_b32_e32 v55, v2
	v_mov_b32_e32 v56, v2
	v_mov_b32_e32 v57, v2
	v_mov_b32_e32 v58, v2
	v_mov_b32_e32 v59, v2
	v_mov_b32_e32 v60, v2
	v_mov_b32_e32 v61, v2
	v_mov_b32_e32 v62, v2
	v_mov_b32_e32 v63, v2
	v_mov_b32_e32 v64, v2
	v_mov_b32_e32 v65, v2
	v_mov_b32_e32 v98, v2
	v_mov_b32_e32 v99, v2
	v_mov_b32_e32 v100, v2
	v_mov_b32_e32 v101, v2
	v_mov_b32_e32 v102, v2
	v_mov_b32_e32 v103, v2
	v_mov_b32_e32 v104, v2
	v_mov_b32_e32 v105, v2
	v_mov_b32_e32 v106, v2
	v_mov_b32_e32 v107, v2
	v_mov_b32_e32 v108, v2
	v_mov_b32_e32 v109, v2
	v_mov_b32_e32 v110, v2
	v_mov_b32_e32 v111, v2
	v_mov_b32_e32 v112, v2
	v_mov_b32_e32 v113, v2
	v_mov_b32_e32 v114, v2
	v_mov_b32_e32 v115, v2
	v_mov_b32_e32 v116, v2
	v_mov_b32_e32 v117, v2
	v_mov_b32_e32 v118, v2
	v_mov_b32_e32 v119, v2
	v_mov_b32_e32 v120, v2
	v_mov_b32_e32 v121, v2
	v_mov_b32_e32 v122, v2
	v_mov_b32_e32 v123, v2
	v_mov_b32_e32 v124, v2
	v_mov_b32_e32 v125, v2
	v_mov_b32_e32 v126, v2
	v_mov_b32_e32 v127, v2
	v_mov_b32_e32 v128, v2
	v_mov_b32_e32 v129, v2
	s_setprio 1
	s_cmp_eq_u64 s[12:13], 0
	s_cbranch_scc1 .Lsp_LBB0_990
	s_setprio 0
.Lsp_LBB0_990:
.LBB0_990:
	ds_read_b128 v[146:149], v154
	ds_read_b128 v[158:161], v154 offset:1024
	ds_read_b128 v[162:165], v154 offset:2048
	ds_read_b128 v[166:169], v154 offset:3072
	ds_read_b128 v[170:173], v155
	ds_read_b128 v[174:177], v155 offset:1024
	ds_read_b128 v[178:181], v155 offset:2048
	ds_read_b128 v[182:185], v155 offset:3072
	s_add_u32 s34, s40, 0xfff00080
	s_addc_u32 s35, s41, -1
	s_cmp_eq_u32 s74, 60
	s_cselect_b32 s35, s23, s35
	s_cselect_b32 s34, s27, s34
	s_cselect_b32 s43, s21, s73
	s_cselect_b32 s42, s39, s72
	s_add_i32 m0, s45, 0xc000
	ds_read_b128 v[186:189], v156
	ds_read_b128 v[190:193], v156 offset:1024
	ds_read_b128 v[194:197], v156 offset:2048
	ds_read_b128 v[198:201], v156 offset:3072
	ds_read_b128 v[202:205], v156 offset:4096
	ds_read_b128 v[206:209], v156 offset:5120
	ds_read_b128 v[210:213], v156 offset:6144
	ds_read_b128 v[214:217], v156 offset:7168
	global_load_lds_dwordx4 v138, s[40:41]
	s_add_i32 m0, s45, 0xe000
	s_nop 0
	global_load_lds_dwordx4 v140, s[40:41]
	s_waitcnt vmcnt(8)
	s_waitcnt lgkmcnt(0)
	s_barrier
; #define PG8_STAGE(bufoff, gbase, voff) do { _Pragma("unroll") for (int _i = 0; _i < 2; ++_i) \
;         __builtin_amdgcn_global_load_lds((const unsigned*)((const char*)(gbase) + (voff)[_i]), (PG8_LAS unsigned*)(lds + (bufoff) + ldsw + _i * 8192), 16, 0, 0); } while (0)
; #define PG8_LDA(dst, b, h) do { _Pragma("unroll") for (int m = 0; m < 4; ++m) _Pragma("unroll") for (int k = 0; k < 2; ++k) dst[m][k] = *(const PG8_LAS bf16x8*)(lds + PG8_SA(b, h) + aoff + m * 2048 + k * 1024); } while (0)
; #define PG8_MMA(ai, bj, At, Bt) do { __builtin_amdgcn_s_setprio(1); _Pragma("unroll") for (int m = 0; m < 4; ++m) _Pragma("unroll") for (int n = 0; n < 2; ++n) _Pragma("unroll") for (int k = 0; k < 2; ++k) \
;         acc[ai][bj][m][n] = __builtin_amdgcn_mfma_f32_16x16x32_bf16(Bt[n][k], At[m][k], acc[ai][bj][m][n], 0, 0, 0); __builtin_amdgcn_s_setprio(0); } while (0)
; #define PG8_WAIT_V(n) asm volatile("s_waitcnt vmcnt(" #n ")" ::: "memory")
; #define PG8_WAIT_L(n) asm volatile("s_waitcnt lgkmcnt(" #n ")" ::: "memory")
; #define PG8_BAR __builtin_amdgcn_s_barrier()
; #define PG8_SCHED __builtin_amdgcn_sched_barrier(0)
; template <class Epi, class Sched, bool ALIGN_EPI = false, bool SP2 = false>
; __device__ __forceinline__ void gemm_phase(PG8_LAS unsigned char* lds, const Gemm g, const Sched& S, const Epi& E) {
;     ...
;             PG8_WAIT_V(8); PG8_WAIT_L(0); PG8_BAR; PG8_MMA(0, 0, At, B0); PG8_MMA(0, 1, At, B1); PG8_BAR; PG8_SCHED;
;             PG8_LDA(At, 0, 1); PG8_STAGE(PG8_SB(0, 0), b2, voffB); PG8_STAGE(PG8_SB(0, 1), b2 + hstepB, voffB); PG8_STAGE(PG8_SA(0, 0), a2, voffA);
;             PG8_WAIT_V(8); PG8_WAIT_L(0); PG8_BAR; PG8_MMA(1, 0, At, B0); PG8_MMA(1, 1, At, B1); PG8_BAR; PG8_SCHED;
	s_waitcnt lgkmcnt(0)
	v_mfma_f32_16x16x32_bf16 v[126:129], v[146:149], v[186:189], v[126:129]
	v_mfma_f32_16x16x32_bf16 v[122:125], v[162:165], v[186:189], v[122:125]
	v_mfma_f32_16x16x32_bf16 v[118:121], v[146:149], v[194:197], v[118:121]
	v_mfma_f32_16x16x32_bf16 v[114:117], v[162:165], v[194:197], v[114:117]
	v_mfma_f32_16x16x32_bf16 v[110:113], v[146:149], v[202:205], v[110:113]
	v_mfma_f32_16x16x32_bf16 v[106:109], v[162:165], v[202:205], v[106:109]
	v_mfma_f32_16x16x32_bf16 v[102:105], v[146:149], v[210:213], v[102:105]
	v_mfma_f32_16x16x32_bf16 v[98:101], v[162:165], v[210:213], v[98:101]
	v_mfma_f32_16x16x32_bf16 v[126:129], v[158:161], v[190:193], v[126:129]
	v_mfma_f32_16x16x32_bf16 v[122:125], v[166:169], v[190:193], v[122:125]
	v_mfma_f32_16x16x32_bf16 v[118:121], v[158:161], v[198:201], v[118:121]
	v_mfma_f32_16x16x32_bf16 v[114:117], v[166:169], v[198:201], v[114:117]
	v_mfma_f32_16x16x32_bf16 v[110:113], v[158:161], v[206:209], v[110:113]
	v_mfma_f32_16x16x32_bf16 v[106:109], v[166:169], v[206:209], v[106:109]
	v_mfma_f32_16x16x32_bf16 v[102:105], v[158:161], v[214:217], v[102:105]
	v_mfma_f32_16x16x32_bf16 v[98:101], v[166:169], v[214:217], v[98:101]
	v_mfma_f32_16x16x32_bf16 v[62:65], v[170:173], v[186:189], v[62:65]
	v_mfma_f32_16x16x32_bf16 v[58:61], v[178:181], v[186:189], v[58:61]
	v_mfma_f32_16x16x32_bf16 v[54:57], v[170:173], v[194:197], v[54:57]
	v_mfma_f32_16x16x32_bf16 v[50:53], v[178:181], v[194:197], v[50:53]
	v_mfma_f32_16x16x32_bf16 v[46:49], v[170:173], v[202:205], v[46:49]
	v_mfma_f32_16x16x32_bf16 v[42:45], v[178:181], v[202:205], v[42:45]
	v_mfma_f32_16x16x32_bf16 v[38:41], v[170:173], v[210:213], v[38:41]
	v_mfma_f32_16x16x32_bf16 v[34:37], v[178:181], v[210:213], v[34:37]
	v_mfma_f32_16x16x32_bf16 v[62:65], v[174:177], v[190:193], v[62:65]
	v_mfma_f32_16x16x32_bf16 v[58:61], v[182:185], v[190:193], v[58:61]
	v_mfma_f32_16x16x32_bf16 v[54:57], v[174:177], v[198:201], v[54:57]
	v_mfma_f32_16x16x32_bf16 v[50:53], v[182:185], v[198:201], v[50:53]
	v_mfma_f32_16x16x32_bf16 v[46:49], v[174:177], v[206:209], v[46:49]
	v_mfma_f32_16x16x32_bf16 v[42:45], v[182:185], v[206:209], v[42:45]
	v_mfma_f32_16x16x32_bf16 v[38:41], v[174:177], v[214:217], v[38:41]
	v_mfma_f32_16x16x32_bf16 v[34:37], v[182:185], v[214:217], v[34:37]
	s_barrier
	s_add_i32 s75, s64, s17
	s_add_u32 s98, s42, 0x80
	s_addc_u32 s99, s43, 0
	s_add_u32 s100, s34, 0x80
	s_addc_u32 s101, s35, 0
	s_mov_b32 m0, s75
	ds_read_b128 v[186:189], v156 offset:16384
	ds_read_b128 v[190:193], v156 offset:17408
	ds_read_b128 v[194:197], v156 offset:18432
	ds_read_b128 v[198:201], v156 offset:19456
	ds_read_b128 v[202:205], v156 offset:20480
	ds_read_b128 v[206:209], v156 offset:21504
	ds_read_b128 v[210:213], v156 offset:22528
	ds_read_b128 v[214:217], v156 offset:23552
	global_load_lds_dwordx4 v134, s[42:43]
	s_add_i32 m0, s75, 0x2000
	s_add_u32 s76, s42, 0x100000
	s_addc_u32 s77, s43, 0
	s_add_i32 s75, s65, s17
	global_load_lds_dwordx4 v130, s[42:43]
	s_mov_b32 m0, s75
	s_nop 0
	global_load_lds_dwordx4 v134, s[76:77]
	s_add_i32 m0, s75, 0x2000
	s_nop 0
	global_load_lds_dwordx4 v130, s[76:77]
	s_mov_b32 m0, s45
	s_nop 0
	global_load_lds_dwordx4 v136, s[34:35]
	s_mov_b32 m0, s46
	s_nop 0
	global_load_lds_dwordx4 v132, s[34:35]
	s_waitcnt vmcnt(8)
	s_waitcnt lgkmcnt(0)
	s_barrier
	s_waitcnt lgkmcnt(0)
	v_mfma_f32_16x16x32_bf16 v[94:97], v[146:149], v[186:189], v[94:97]
	v_mfma_f32_16x16x32_bf16 v[90:93], v[162:165], v[186:189], v[90:93]
	v_mfma_f32_16x16x32_bf16 v[86:89], v[146:149], v[194:197], v[86:89]
	v_mfma_f32_16x16x32_bf16 v[82:85], v[162:165], v[194:197], v[82:85]
	v_mfma_f32_16x16x32_bf16 v[78:81], v[146:149], v[202:205], v[78:81]
	v_mfma_f32_16x16x32_bf16 v[74:77], v[162:165], v[202:205], v[74:77]
	v_mfma_f32_16x16x32_bf16 v[70:73], v[146:149], v[210:213], v[70:73]
	v_mfma_f32_16x16x32_bf16 v[66:69], v[162:165], v[210:213], v[66:69]
	v_mfma_f32_16x16x32_bf16 v[94:97], v[158:161], v[190:193], v[94:97]
	v_mfma_f32_16x16x32_bf16 v[90:93], v[166:169], v[190:193], v[90:93]
	v_mfma_f32_16x16x32_bf16 v[86:89], v[158:161], v[198:201], v[86:89]
	v_mfma_f32_16x16x32_bf16 v[82:85], v[166:169], v[198:201], v[82:85]
	v_mfma_f32_16x16x32_bf16 v[78:81], v[158:161], v[206:209], v[78:81]
	v_mfma_f32_16x16x32_bf16 v[74:77], v[166:169], v[206:209], v[74:77]
	v_mfma_f32_16x16x32_bf16 v[70:73], v[158:161], v[214:217], v[70:73]
	v_mfma_f32_16x16x32_bf16 v[66:69], v[166:169], v[214:217], v[66:69]
	v_mfma_f32_16x16x32_bf16 v[30:33], v[170:173], v[186:189], v[30:33]
	v_mfma_f32_16x16x32_bf16 v[26:29], v[178:181], v[186:189], v[26:29]
	v_mfma_f32_16x16x32_bf16 v[22:25], v[170:173], v[194:197], v[22:25]
	v_mfma_f32_16x16x32_bf16 v[18:21], v[178:181], v[194:197], v[18:21]
	v_mfma_f32_16x16x32_bf16 v[14:17], v[170:173], v[202:205], v[14:17]
	v_mfma_f32_16x16x32_bf16 v[10:13], v[178:181], v[202:205], v[10:13]
	v_mfma_f32_16x16x32_bf16 v[6:9], v[170:173], v[210:213], v[6:9]
	v_mfma_f32_16x16x32_bf16 v[2:5], v[178:181], v[210:213], v[2:5]
	v_mfma_f32_16x16x32_bf16 v[30:33], v[174:177], v[190:193], v[30:33]
	v_mfma_f32_16x16x32_bf16 v[26:29], v[182:185], v[190:193], v[26:29]
	v_mfma_f32_16x16x32_bf16 v[22:25], v[174:177], v[198:201], v[22:25]
	v_mfma_f32_16x16x32_bf16 v[18:21], v[182:185], v[198:201], v[18:21]
	v_mfma_f32_16x16x32_bf16 v[14:17], v[174:177], v[206:209], v[14:17]
	v_mfma_f32_16x16x32_bf16 v[10:13], v[182:185], v[206:209], v[10:13]
	v_mfma_f32_16x16x32_bf16 v[6:9], v[174:177], v[214:217], v[6:9]
	v_mfma_f32_16x16x32_bf16 v[2:5], v[182:185], v[214:217], v[2:5]
	s_barrier
; #define PG8_STAGE(bufoff, gbase, voff) do { _Pragma("unroll") for (int _i = 0; _i < 2; ++_i) \
;         __builtin_amdgcn_global_load_lds((const unsigned*)((const char*)(gbase) + (voff)[_i]), (PG8_LAS unsigned*)(lds + (bufoff) + ldsw + _i * 8192), 16, 0, 0); } while (0)
; #define PG8_LDA(dst, b, h) do { _Pragma("unroll") for (int m = 0; m < 4; ++m) _Pragma("unroll") for (int k = 0; k < 2; ++k) dst[m][k] = *(const PG8_LAS bf16x8*)(lds + PG8_SA(b, h) + aoff + m * 2048 + k * 1024); } while (0)
; #define PG8_LDB(dst, b, h) do { _Pragma("unroll") for (int n = 0; n < 2; ++n) _Pragma("unroll") for (int k = 0; k < 2; ++k) dst[n][k] = *(const PG8_LAS bf16x8*)(lds + PG8_SB(b, h) + boff + n * 2048 + k * 1024); } while (0)
; #define PG8_MMA(ai, bj, At, Bt) do { __builtin_amdgcn_s_setprio(1); _Pragma("unroll") for (int m = 0; m < 4; ++m) _Pragma("unroll") for (int n = 0; n < 2; ++n) _Pragma("unroll") for (int k = 0; k < 2; ++k) \
;         acc[ai][bj][m][n] = __builtin_amdgcn_mfma_f32_16x16x32_bf16(Bt[n][k], At[m][k], acc[ai][bj][m][n], 0, 0, 0); __builtin_amdgcn_s_setprio(0); } while (0)
; #define PG8_WAIT_V(n) asm volatile("s_waitcnt vmcnt(" #n ")" ::: "memory")
; #define PG8_WAIT_L(n) asm volatile("s_waitcnt lgkmcnt(" #n ")" ::: "memory")
; #define PG8_BAR __builtin_amdgcn_s_barrier()
; #define PG8_SCHED __builtin_amdgcn_sched_barrier(0)
; template <class Epi, class Sched, bool ALIGN_EPI = false, bool SP2 = false>
; __device__ __forceinline__ void gemm_phase(PG8_LAS unsigned char* lds, const Gemm g, const Sched& S, const Epi& E) {
;     ...
;         for (int t = 0; t < nt; t += 2) {
;     ...
;             PG8_LDB(B0, 1, 0); PG8_LDB(B1, 1, 1); PG8_SCHED; PG8_LDA(At, 1, 0); PG8_STAGE(PG8_SA(0, 1), a2 + hstepA, voffA);
;             PG8_WAIT_V(8); PG8_WAIT_L(0); PG8_BAR; PG8_MMA(0, 0, At, B0); PG8_MMA(0, 1, At, B1); PG8_BAR; PG8_SCHED;
;             PG8_LDA(At, 1, 1); PG8_STAGE(PG8_SB(1, 0), b3, voffB); PG8_STAGE(PG8_SB(1, 1), b3 + hstepB, voffB); PG8_STAGE(PG8_SA(1, 0), a3, voffA);
;             PG8_WAIT_V(8); PG8_WAIT_L(0); PG8_BAR; PG8_MMA(1, 0, At, B0); PG8_MMA(1, 1, At, B1); PG8_BAR; PG8_SCHED;
	s_add_i32 s75, 0, 0x18000
	v_add_u32_e32 v157, s75, v152
	s_add_i32 s76, 0, 0x1c000
	ds_read_b128 v[146:149], v157
	ds_read_b128 v[158:161], v157 offset:1024
	ds_read_b128 v[162:165], v157 offset:2048
	ds_read_b128 v[166:169], v157 offset:3072
	v_add_u32_e32 v157, s76, v152
	ds_read_b128 v[170:173], v157
	ds_read_b128 v[174:177], v157 offset:1024
	ds_read_b128 v[178:181], v157 offset:2048
	ds_read_b128 v[182:185], v157 offset:3072
	s_add_u32 s34, s34, 0x100000
	s_addc_u32 s35, s35, 0
	s_mov_b32 m0, s47
	ds_read_b128 v[186:189], v156 offset:32768
	ds_read_b128 v[190:193], v156 offset:33792
	ds_read_b128 v[194:197], v156 offset:34816
	ds_read_b128 v[198:201], v156 offset:35840
	ds_read_b128 v[202:205], v156 offset:36864
	ds_read_b128 v[206:209], v156 offset:37888
	ds_read_b128 v[210:213], v156 offset:38912
	ds_read_b128 v[214:217], v156 offset:39936
	global_load_lds_dwordx4 v136, s[34:35]
	s_mov_b32 m0, s48
	s_nop 0
	global_load_lds_dwordx4 v132, s[34:35]
	s_waitcnt vmcnt(8)
	s_waitcnt lgkmcnt(0)
	s_barrier
	s_waitcnt lgkmcnt(0)
	v_mfma_f32_16x16x32_bf16 v[126:129], v[146:149], v[186:189], v[126:129]
	v_mfma_f32_16x16x32_bf16 v[122:125], v[162:165], v[186:189], v[122:125]
	v_mfma_f32_16x16x32_bf16 v[118:121], v[146:149], v[194:197], v[118:121]
	v_mfma_f32_16x16x32_bf16 v[114:117], v[162:165], v[194:197], v[114:117]
	v_mfma_f32_16x16x32_bf16 v[110:113], v[146:149], v[202:205], v[110:113]
	v_mfma_f32_16x16x32_bf16 v[106:109], v[162:165], v[202:205], v[106:109]
	v_mfma_f32_16x16x32_bf16 v[102:105], v[146:149], v[210:213], v[102:105]
	v_mfma_f32_16x16x32_bf16 v[98:101], v[162:165], v[210:213], v[98:101]
	v_mfma_f32_16x16x32_bf16 v[126:129], v[158:161], v[190:193], v[126:129]
	v_mfma_f32_16x16x32_bf16 v[122:125], v[166:169], v[190:193], v[122:125]
	v_mfma_f32_16x16x32_bf16 v[118:121], v[158:161], v[198:201], v[118:121]
	v_mfma_f32_16x16x32_bf16 v[114:117], v[166:169], v[198:201], v[114:117]
	v_mfma_f32_16x16x32_bf16 v[110:113], v[158:161], v[206:209], v[110:113]
	v_mfma_f32_16x16x32_bf16 v[106:109], v[166:169], v[206:209], v[106:109]
	v_mfma_f32_16x16x32_bf16 v[102:105], v[158:161], v[214:217], v[102:105]
	v_mfma_f32_16x16x32_bf16 v[98:101], v[166:169], v[214:217], v[98:101]
	v_mfma_f32_16x16x32_bf16 v[62:65], v[170:173], v[186:189], v[62:65]
	v_mfma_f32_16x16x32_bf16 v[58:61], v[178:181], v[186:189], v[58:61]
	v_mfma_f32_16x16x32_bf16 v[54:57], v[170:173], v[194:197], v[54:57]
	v_mfma_f32_16x16x32_bf16 v[50:53], v[178:181], v[194:197], v[50:53]
	v_mfma_f32_16x16x32_bf16 v[46:49], v[170:173], v[202:205], v[46:49]
	v_mfma_f32_16x16x32_bf16 v[42:45], v[178:181], v[202:205], v[42:45]
	v_mfma_f32_16x16x32_bf16 v[38:41], v[170:173], v[210:213], v[38:41]
	v_mfma_f32_16x16x32_bf16 v[34:37], v[178:181], v[210:213], v[34:37]
	v_mfma_f32_16x16x32_bf16 v[62:65], v[174:177], v[190:193], v[62:65]
	v_mfma_f32_16x16x32_bf16 v[58:61], v[182:185], v[190:193], v[58:61]
	v_mfma_f32_16x16x32_bf16 v[54:57], v[174:177], v[198:201], v[54:57]
	v_mfma_f32_16x16x32_bf16 v[50:53], v[182:185], v[198:201], v[50:53]
	v_mfma_f32_16x16x32_bf16 v[46:49], v[174:177], v[206:209], v[46:49]
	v_mfma_f32_16x16x32_bf16 v[42:45], v[182:185], v[206:209], v[42:45]
	v_mfma_f32_16x16x32_bf16 v[38:41], v[174:177], v[214:217], v[38:41]
	v_mfma_f32_16x16x32_bf16 v[34:37], v[182:185], v[214:217], v[34:37]
	s_barrier
	s_add_i32 s34, s75, s17
	s_mov_b32 m0, s34
	ds_read_b128 v[186:189], v156 offset:49152
	ds_read_b128 v[190:193], v156 offset:50176
	ds_read_b128 v[194:197], v156 offset:51200
	ds_read_b128 v[198:201], v156 offset:52224
	ds_read_b128 v[202:205], v156 offset:53248
	ds_read_b128 v[206:209], v156 offset:54272
	ds_read_b128 v[210:213], v156 offset:55296
	ds_read_b128 v[214:217], v156 offset:56320
	global_load_lds_dwordx4 v134, s[98:99]
	s_add_i32 m0, s34, 0x2000
	s_add_u32 s34, s42, 0x100080
	s_addc_u32 s35, s43, 0
	s_add_i32 s42, s76, s17
	global_load_lds_dwordx4 v130, s[98:99]
	s_mov_b32 m0, s42
	s_nop 0
	global_load_lds_dwordx4 v134, s[34:35]
	s_add_i32 m0, s42, 0x2000
	s_nop 0
	global_load_lds_dwordx4 v130, s[34:35]
	s_mov_b32 m0, s52
	s_nop 0
	global_load_lds_dwordx4 v136, s[100:101]
	s_mov_b32 m0, s53
	s_nop 0
	global_load_lds_dwordx4 v132, s[100:101]
	s_waitcnt vmcnt(8)
	s_waitcnt lgkmcnt(0)
	s_barrier
	s_waitcnt lgkmcnt(0)
	v_mfma_f32_16x16x32_bf16 v[94:97], v[146:149], v[186:189], v[94:97]
	v_mfma_f32_16x16x32_bf16 v[90:93], v[162:165], v[186:189], v[90:93]
	v_mfma_f32_16x16x32_bf16 v[86:89], v[146:149], v[194:197], v[86:89]
	v_mfma_f32_16x16x32_bf16 v[82:85], v[162:165], v[194:197], v[82:85]
	v_mfma_f32_16x16x32_bf16 v[78:81], v[146:149], v[202:205], v[78:81]
	v_mfma_f32_16x16x32_bf16 v[74:77], v[162:165], v[202:205], v[74:77]
	v_mfma_f32_16x16x32_bf16 v[70:73], v[146:149], v[210:213], v[70:73]
	v_mfma_f32_16x16x32_bf16 v[66:69], v[162:165], v[210:213], v[66:69]
	v_mfma_f32_16x16x32_bf16 v[94:97], v[158:161], v[190:193], v[94:97]
	v_mfma_f32_16x16x32_bf16 v[90:93], v[166:169], v[190:193], v[90:93]
	v_mfma_f32_16x16x32_bf16 v[86:89], v[158:161], v[198:201], v[86:89]
	v_mfma_f32_16x16x32_bf16 v[82:85], v[166:169], v[198:201], v[82:85]
	v_mfma_f32_16x16x32_bf16 v[78:81], v[158:161], v[206:209], v[78:81]
	v_mfma_f32_16x16x32_bf16 v[74:77], v[166:169], v[206:209], v[74:77]
	v_mfma_f32_16x16x32_bf16 v[70:73], v[158:161], v[214:217], v[70:73]
	v_mfma_f32_16x16x32_bf16 v[66:69], v[166:169], v[214:217], v[66:69]
	v_mfma_f32_16x16x32_bf16 v[30:33], v[170:173], v[186:189], v[30:33]
	v_mfma_f32_16x16x32_bf16 v[26:29], v[178:181], v[186:189], v[26:29]
	v_mfma_f32_16x16x32_bf16 v[22:25], v[170:173], v[194:197], v[22:25]
	v_mfma_f32_16x16x32_bf16 v[18:21], v[178:181], v[194:197], v[18:21]
	v_mfma_f32_16x16x32_bf16 v[14:17], v[170:173], v[202:205], v[14:17]
	v_mfma_f32_16x16x32_bf16 v[10:13], v[178:181], v[202:205], v[10:13]
	v_mfma_f32_16x16x32_bf16 v[6:9], v[170:173], v[210:213], v[6:9]
	v_mfma_f32_16x16x32_bf16 v[2:5], v[178:181], v[210:213], v[2:5]
	v_mfma_f32_16x16x32_bf16 v[30:33], v[174:177], v[190:193], v[30:33]
	v_mfma_f32_16x16x32_bf16 v[26:29], v[182:185], v[190:193], v[26:29]
	v_mfma_f32_16x16x32_bf16 v[22:25], v[174:177], v[198:201], v[22:25]
	v_mfma_f32_16x16x32_bf16 v[18:21], v[182:185], v[198:201], v[18:21]
	v_mfma_f32_16x16x32_bf16 v[14:17], v[174:177], v[206:209], v[14:17]
	v_mfma_f32_16x16x32_bf16 v[10:13], v[182:185], v[206:209], v[10:13]
	v_mfma_f32_16x16x32_bf16 v[6:9], v[174:177], v[214:217], v[6:9]
	v_mfma_f32_16x16x32_bf16 v[2:5], v[182:185], v[214:217], v[2:5]
	s_barrier
	s_add_i32 s74, s74, 2
	s_add_u32 s40, s40, 0x100
	s_addc_u32 s41, s41, 0
	s_add_u32 s72, s72, 0x100
	s_addc_u32 s73, s73, 0
	s_cmp_gt_u32 s74, 61
	s_cbranch_scc0 .LBB0_990
	s_setprio 0
	s_and_b64 vcc, exec, s[12:13]
	s_cbranch_vccz .LBB0_993
	s_barrier

; #define PG8_STAGE(bufoff, gbase, voff) do { _Pragma("unroll") for (int _i = 0; _i < 2; ++_i) \
;         __builtin_amdgcn_global_load_lds((const unsigned*)((const char*)(gbase) + (voff)[_i]), (PG8_LAS unsigned*)(lds + (bufoff) + ldsw + _i * 8192), 16, 0, 0); } while (0)
; #define PG8_LDA(dst, b, h) do { _Pragma("unroll") for (int m = 0; m < 4; ++m) _Pragma("unroll") for (int k = 0; k < 2; ++k) dst[m][k] = *(const PG8_LAS bf16x8*)(lds + PG8_SA(b, h) + aoff + m * 2048 + k * 1024); } while (0)
; #define PG8_LDB(dst, b, h) do { _Pragma("unroll") for (int n = 0; n < 2; ++n) _Pragma("unroll") for (int k = 0; k < 2; ++k) dst[n][k] = *(const PG8_LAS bf16x8*)(lds + PG8_SB(b, h) + boff + n * 2048 + k * 1024); } while (0)
; #define PG8_MMA(ai, bj, At, Bt) do { __builtin_amdgcn_s_setprio(1); _Pragma("unroll") for (int m = 0; m < 4; ++m) _Pragma("unroll") for (int n = 0; n < 2; ++n) _Pragma("unroll") for (int k = 0; k < 2; ++k) \
;         acc[ai][bj][m][n] = __builtin_amdgcn_mfma_f32_16x16x32_bf16(Bt[n][k], At[m][k], acc[ai][bj][m][n], 0, 0, 0); __builtin_amdgcn_s_setprio(0); } while (0)
; #define PG8_WAIT_V(n) asm volatile("s_waitcnt vmcnt(" #n ")" ::: "memory")
; #define PG8_WAIT_L(n) asm volatile("s_waitcnt lgkmcnt(" #n ")" ::: "memory")
; #define PG8_BAR __builtin_amdgcn_s_barrier()
; #define PG8_SCHED __builtin_amdgcn_sched_barrier(0)
; template <class Epi, class Sched, bool ALIGN_EPI = false, bool SP2 = false>
; __device__ __forceinline__ void gemm_phase(PG8_LAS unsigned char* lds, const Gemm g, const Sched& S, const Epi& E) {
;     ...
;             PG8_LDB(B0, 0, 0); PG8_LDB(B1, 0, 1); PG8_SCHED; PG8_LDA(At, 0, 0); PG8_STAGE(PG8_SA(1, 1), a1 + hstepA, voffA);
;             PG8_WAIT_V(8); PG8_WAIT_L(0); PG8_BAR; PG8_MMA(0, 0, At, B0); PG8_MMA(0, 1, At, B1); PG8_BAR; PG8_SCHED;
;             PG8_LDA(At, 0, 1); PG8_STAGE(PG8_SB(0, 0), b2, voffB); PG8_STAGE(PG8_SB(0, 1), b2 + hstepB, voffB); PG8_STAGE(PG8_SA(0, 0), a2, voffA);
;             PG8_WAIT_V(8); PG8_WAIT_L(0); PG8_BAR; PG8_MMA(1, 0, At, B0); PG8_MMA(1, 1, At, B1); PG8_BAR; PG8_SCHED;
.Lp11_st_skip:
	s_setprio 1
	s_cmp_eq_u64 s[14:15], 0
	s_cbranch_scc1 .Lsp_LBB0_1127
	s_setprio 0
.Lsp_LBB0_1127:
.LBB0_1127:
	ds_read_b128 v[130:133], v203
	ds_read_b128 v[134:137], v203 offset:1024
	ds_read_b128 v[138:141], v203 offset:2048
	ds_read_b128 v[142:145], v203 offset:3072
	ds_read_b128 v[146:149], v205
	ds_read_b128 v[150:153], v205 offset:1024
	ds_read_b128 v[154:157], v205 offset:2048
	ds_read_b128 v[158:161], v205 offset:3072
	s_add_u32 s34, s40, 0xfff00080
	s_addc_u32 s35, s41, -1
	s_cmp_eq_u32 s53, 60
	s_cselect_b32 s35, s25, s35
	s_cselect_b32 s34, s26, s34
	s_cselect_b32 s43, s23, s52
	s_cselect_b32 s42, s27, s45
	s_add_i32 m0, s47, 0xc000
	ds_read_b128 v[162:165], v207
	ds_read_b128 v[166:169], v207 offset:1024
	ds_read_b128 v[170:173], v207 offset:2048
	ds_read_b128 v[174:177], v207 offset:3072
	ds_read_b128 v[196:199], v207 offset:4096
	ds_read_b128 v[208:211], v207 offset:5120
	ds_read_b128 v[212:215], v207 offset:6144
	ds_read_b128 v[216:219], v207 offset:7168
	global_load_lds_dwordx4 v188, s[40:41]
	s_add_i32 m0, s47, 0xe000
	s_nop 0
	global_load_lds_dwordx4 v190, s[40:41]
	s_waitcnt vmcnt(8)
	s_waitcnt lgkmcnt(0)
	s_barrier
	s_waitcnt lgkmcnt(0)
	v_mfma_f32_16x16x32_bf16 v[122:125], v[130:133], v[162:165], v[122:125]
	v_mfma_f32_16x16x32_bf16 v[118:121], v[138:141], v[162:165], v[118:121]
	v_mfma_f32_16x16x32_bf16 v[106:109], v[130:133], v[170:173], v[106:109]
	v_mfma_f32_16x16x32_bf16 v[102:105], v[138:141], v[170:173], v[102:105]
	v_mfma_f32_16x16x32_bf16 v[90:93], v[130:133], v[196:199], v[90:93]
	v_mfma_f32_16x16x32_bf16 v[86:89], v[138:141], v[196:199], v[86:89]
	v_mfma_f32_16x16x32_bf16 v[74:77], v[130:133], v[212:215], v[74:77]
	v_mfma_f32_16x16x32_bf16 v[70:73], v[138:141], v[212:215], v[70:73]
	v_mfma_f32_16x16x32_bf16 v[122:125], v[134:137], v[166:169], v[122:125]
	v_mfma_f32_16x16x32_bf16 v[118:121], v[142:145], v[166:169], v[118:121]
	v_mfma_f32_16x16x32_bf16 v[106:109], v[134:137], v[174:177], v[106:109]
	v_mfma_f32_16x16x32_bf16 v[102:105], v[142:145], v[174:177], v[102:105]
	v_mfma_f32_16x16x32_bf16 v[90:93], v[134:137], v[208:211], v[90:93]
	v_mfma_f32_16x16x32_bf16 v[86:89], v[142:145], v[208:211], v[86:89]
	v_mfma_f32_16x16x32_bf16 v[74:77], v[134:137], v[216:219], v[74:77]
	v_mfma_f32_16x16x32_bf16 v[70:73], v[142:145], v[216:219], v[70:73]
	v_mfma_f32_16x16x32_bf16 v[126:129], v[146:149], v[162:165], v[126:129]
	v_mfma_f32_16x16x32_bf16 v[114:117], v[154:157], v[162:165], v[114:117]
	v_mfma_f32_16x16x32_bf16 v[110:113], v[146:149], v[170:173], v[110:113]
	v_mfma_f32_16x16x32_bf16 v[98:101], v[154:157], v[170:173], v[98:101]
	v_mfma_f32_16x16x32_bf16 v[94:97], v[146:149], v[196:199], v[94:97]
	v_mfma_f32_16x16x32_bf16 v[82:85], v[154:157], v[196:199], v[82:85]
	v_mfma_f32_16x16x32_bf16 v[78:81], v[146:149], v[212:215], v[78:81]
	v_mfma_f32_16x16x32_bf16 v[66:69], v[154:157], v[212:215], v[66:69]
	v_mfma_f32_16x16x32_bf16 v[126:129], v[150:153], v[166:169], v[126:129]
	v_mfma_f32_16x16x32_bf16 v[114:117], v[158:161], v[166:169], v[114:117]
	v_mfma_f32_16x16x32_bf16 v[110:113], v[150:153], v[174:177], v[110:113]
	v_mfma_f32_16x16x32_bf16 v[98:101], v[158:161], v[174:177], v[98:101]
	v_mfma_f32_16x16x32_bf16 v[94:97], v[150:153], v[208:211], v[94:97]
	v_mfma_f32_16x16x32_bf16 v[82:85], v[158:161], v[208:211], v[82:85]
	v_mfma_f32_16x16x32_bf16 v[78:81], v[150:153], v[216:219], v[78:81]
	v_mfma_f32_16x16x32_bf16 v[66:69], v[158:161], v[216:219], v[66:69]
	s_barrier
	s_add_i32 s73, s68, s17
	s_add_u32 s98, s42, 0x80
	s_addc_u32 s99, s43, 0
	s_add_u32 s100, s34, 0x80
	s_addc_u32 s101, s35, 0
	s_mov_b32 m0, s73
	ds_read_b128 v[162:165], v207 offset:16384
	ds_read_b128 v[166:169], v207 offset:17408
	ds_read_b128 v[170:173], v207 offset:18432
	ds_read_b128 v[174:177], v207 offset:19456
	ds_read_b128 v[196:199], v207 offset:20480
	ds_read_b128 v[208:211], v207 offset:21504
	ds_read_b128 v[212:215], v207 offset:22528
	ds_read_b128 v[216:219], v207 offset:23552
	global_load_lds_dwordx4 v182, s[42:43]
	s_add_i32 m0, s73, 0x2000
	s_add_u32 s74, s42, 0x100000
	s_addc_u32 s75, s43, 0
	s_add_i32 s73, s69, s17
	global_load_lds_dwordx4 v178, s[42:43]
	s_mov_b32 m0, s73
	s_nop 0
	global_load_lds_dwordx4 v182, s[74:75]
	s_add_i32 m0, s73, 0x2000
	s_nop 0
	global_load_lds_dwordx4 v178, s[74:75]
	s_mov_b32 m0, s47
	s_nop 0
	global_load_lds_dwordx4 v184, s[34:35]
	s_mov_b32 m0, s48
	s_nop 0
	global_load_lds_dwordx4 v180, s[34:35]
	s_waitcnt vmcnt(8)
	s_waitcnt lgkmcnt(0)
	s_barrier
	s_waitcnt lgkmcnt(0)
	v_mfma_f32_16x16x32_bf16 v[58:61], v[130:133], v[162:165], v[58:61]
	v_mfma_f32_16x16x32_bf16 v[54:57], v[138:141], v[162:165], v[54:57]
	v_mfma_f32_16x16x32_bf16 v[42:45], v[130:133], v[170:173], v[42:45]
	v_mfma_f32_16x16x32_bf16 v[38:41], v[138:141], v[170:173], v[38:41]
	v_mfma_f32_16x16x32_bf16 v[26:29], v[130:133], v[196:199], v[26:29]
	v_mfma_f32_16x16x32_bf16 v[22:25], v[138:141], v[196:199], v[22:25]
	v_mfma_f32_16x16x32_bf16 v[10:13], v[130:133], v[212:215], v[10:13]
	v_mfma_f32_16x16x32_bf16 v[6:9], v[138:141], v[212:215], v[6:9]
	v_mfma_f32_16x16x32_bf16 v[58:61], v[134:137], v[166:169], v[58:61]
	v_mfma_f32_16x16x32_bf16 v[54:57], v[142:145], v[166:169], v[54:57]
	v_mfma_f32_16x16x32_bf16 v[42:45], v[134:137], v[174:177], v[42:45]
	v_mfma_f32_16x16x32_bf16 v[38:41], v[142:145], v[174:177], v[38:41]
	v_mfma_f32_16x16x32_bf16 v[26:29], v[134:137], v[208:211], v[26:29]
	v_mfma_f32_16x16x32_bf16 v[22:25], v[142:145], v[208:211], v[22:25]
	v_mfma_f32_16x16x32_bf16 v[10:13], v[134:137], v[216:219], v[10:13]
	v_mfma_f32_16x16x32_bf16 v[6:9], v[142:145], v[216:219], v[6:9]
	v_mfma_f32_16x16x32_bf16 v[62:65], v[146:149], v[162:165], v[62:65]
	v_mfma_f32_16x16x32_bf16 v[50:53], v[154:157], v[162:165], v[50:53]
	v_mfma_f32_16x16x32_bf16 v[46:49], v[146:149], v[170:173], v[46:49]
	v_mfma_f32_16x16x32_bf16 v[34:37], v[154:157], v[170:173], v[34:37]
	v_mfma_f32_16x16x32_bf16 v[30:33], v[146:149], v[196:199], v[30:33]
	v_mfma_f32_16x16x32_bf16 v[18:21], v[154:157], v[196:199], v[18:21]
	v_mfma_f32_16x16x32_bf16 v[14:17], v[146:149], v[212:215], v[14:17]
	v_mfma_f32_16x16x32_bf16 v[2:5], v[154:157], v[212:215], v[2:5]
	v_mfma_f32_16x16x32_bf16 v[62:65], v[150:153], v[166:169], v[62:65]
	v_mfma_f32_16x16x32_bf16 v[50:53], v[158:161], v[166:169], v[50:53]
	v_mfma_f32_16x16x32_bf16 v[46:49], v[150:153], v[174:177], v[46:49]
	v_mfma_f32_16x16x32_bf16 v[34:37], v[158:161], v[174:177], v[34:37]
	v_mfma_f32_16x16x32_bf16 v[30:33], v[150:153], v[208:211], v[30:33]
	v_mfma_f32_16x16x32_bf16 v[18:21], v[158:161], v[208:211], v[18:21]
	v_mfma_f32_16x16x32_bf16 v[14:17], v[150:153], v[216:219], v[14:17]
	v_mfma_f32_16x16x32_bf16 v[2:5], v[158:161], v[216:219], v[2:5]
	s_barrier
; #define PG8_STAGE(bufoff, gbase, voff) do { _Pragma("unroll") for (int _i = 0; _i < 2; ++_i) \
;         __builtin_amdgcn_global_load_lds((const unsigned*)((const char*)(gbase) + (voff)[_i]), (PG8_LAS unsigned*)(lds + (bufoff) + ldsw + _i * 8192), 16, 0, 0); } while (0)
; #define PG8_LDA(dst, b, h) do { _Pragma("unroll") for (int m = 0; m < 4; ++m) _Pragma("unroll") for (int k = 0; k < 2; ++k) dst[m][k] = *(const PG8_LAS bf16x8*)(lds + PG8_SA(b, h) + aoff + m * 2048 + k * 1024); } while (0)
; #define PG8_LDB(dst, b, h) do { _Pragma("unroll") for (int n = 0; n < 2; ++n) _Pragma("unroll") for (int k = 0; k < 2; ++k) dst[n][k] = *(const PG8_LAS bf16x8*)(lds + PG8_SB(b, h) + boff + n * 2048 + k * 1024); } while (0)
; #define PG8_MMA(ai, bj, At, Bt) do { __builtin_amdgcn_s_setprio(1); _Pragma("unroll") for (int m = 0; m < 4; ++m) _Pragma("unroll") for (int n = 0; n < 2; ++n) _Pragma("unroll") for (int k = 0; k < 2; ++k) \
;         acc[ai][bj][m][n] = __builtin_amdgcn_mfma_f32_16x16x32_bf16(Bt[n][k], At[m][k], acc[ai][bj][m][n], 0, 0, 0); __builtin_amdgcn_s_setprio(0); } while (0)
; #define PG8_WAIT_V(n) asm volatile("s_waitcnt vmcnt(" #n ")" ::: "memory")
; #define PG8_WAIT_L(n) asm volatile("s_waitcnt lgkmcnt(" #n ")" ::: "memory")
; #define PG8_BAR __builtin_amdgcn_s_barrier()
; #define PG8_SCHED __builtin_amdgcn_sched_barrier(0)
; template <class Epi, class Sched, bool ALIGN_EPI = false, bool SP2 = false>
; __device__ __forceinline__ void gemm_phase(PG8_LAS unsigned char* lds, const Gemm g, const Sched& S, const Epi& E) {
;     ...
;         for (int t = 0; t < nt; t += 2) {
;     ...
;             PG8_LDB(B0, 1, 0); PG8_LDB(B1, 1, 1); PG8_SCHED; PG8_LDA(At, 1, 0); PG8_STAGE(PG8_SA(0, 1), a2 + hstepA, voffA);
;             PG8_WAIT_V(8); PG8_WAIT_L(0); PG8_BAR; PG8_MMA(0, 0, At, B0); PG8_MMA(0, 1, At, B1); PG8_BAR; PG8_SCHED;
;             PG8_LDA(At, 1, 1); PG8_STAGE(PG8_SB(1, 0), b3, voffB); PG8_STAGE(PG8_SB(1, 1), b3 + hstepB, voffB); PG8_STAGE(PG8_SA(1, 0), a3, voffA);
;             PG8_WAIT_V(8); PG8_WAIT_L(0); PG8_BAR; PG8_MMA(1, 0, At, B0); PG8_MMA(1, 1, At, B1); PG8_BAR; PG8_SCHED;
	s_add_i32 s73, 0, 0x18000
	s_add_i32 s74, 0, 0x1c000
	v_add_u32_e32 v142, s73, v1
	v_add_u32_e32 v158, s74, v1
	ds_read_b128 v[130:133], v142
	ds_read_b128 v[134:137], v142 offset:1024
	ds_read_b128 v[138:141], v142 offset:2048
	ds_read_b128 v[142:145], v142 offset:3072
	ds_read_b128 v[146:149], v158
	ds_read_b128 v[150:153], v158 offset:1024
	ds_read_b128 v[154:157], v158 offset:2048
	ds_read_b128 v[158:161], v158 offset:3072
	s_add_u32 s34, s34, 0x100000
	s_addc_u32 s35, s35, 0
	s_mov_b32 m0, s49
	ds_read_b128 v[162:165], v207 offset:32768
	ds_read_b128 v[166:169], v207 offset:33792
	ds_read_b128 v[170:173], v207 offset:34816
	ds_read_b128 v[174:177], v207 offset:35840
	ds_read_b128 v[196:199], v207 offset:36864
	ds_read_b128 v[208:211], v207 offset:37888
	ds_read_b128 v[212:215], v207 offset:38912
	ds_read_b128 v[216:219], v207 offset:39936
	global_load_lds_dwordx4 v184, s[34:35]
	s_mov_b32 m0, s60
	s_nop 0
	global_load_lds_dwordx4 v180, s[34:35]
	s_waitcnt vmcnt(8)
	s_waitcnt lgkmcnt(0)
	s_barrier
	s_waitcnt lgkmcnt(0)
	v_mfma_f32_16x16x32_bf16 v[122:125], v[130:133], v[162:165], v[122:125]
	v_mfma_f32_16x16x32_bf16 v[118:121], v[138:141], v[162:165], v[118:121]
	v_mfma_f32_16x16x32_bf16 v[106:109], v[130:133], v[170:173], v[106:109]
	v_mfma_f32_16x16x32_bf16 v[102:105], v[138:141], v[170:173], v[102:105]
	v_mfma_f32_16x16x32_bf16 v[90:93], v[130:133], v[196:199], v[90:93]
	v_mfma_f32_16x16x32_bf16 v[86:89], v[138:141], v[196:199], v[86:89]
	v_mfma_f32_16x16x32_bf16 v[74:77], v[130:133], v[212:215], v[74:77]
	v_mfma_f32_16x16x32_bf16 v[70:73], v[138:141], v[212:215], v[70:73]
	v_mfma_f32_16x16x32_bf16 v[122:125], v[134:137], v[166:169], v[122:125]
	v_mfma_f32_16x16x32_bf16 v[118:121], v[142:145], v[166:169], v[118:121]
	v_mfma_f32_16x16x32_bf16 v[106:109], v[134:137], v[174:177], v[106:109]
	v_mfma_f32_16x16x32_bf16 v[102:105], v[142:145], v[174:177], v[102:105]
	v_mfma_f32_16x16x32_bf16 v[90:93], v[134:137], v[208:211], v[90:93]
	v_mfma_f32_16x16x32_bf16 v[86:89], v[142:145], v[208:211], v[86:89]
	v_mfma_f32_16x16x32_bf16 v[74:77], v[134:137], v[216:219], v[74:77]
	v_mfma_f32_16x16x32_bf16 v[70:73], v[142:145], v[216:219], v[70:73]
	v_mfma_f32_16x16x32_bf16 v[126:129], v[146:149], v[162:165], v[126:129]
	v_mfma_f32_16x16x32_bf16 v[114:117], v[154:157], v[162:165], v[114:117]
	v_mfma_f32_16x16x32_bf16 v[110:113], v[146:149], v[170:173], v[110:113]
	v_mfma_f32_16x16x32_bf16 v[98:101], v[154:157], v[170:173], v[98:101]
	v_mfma_f32_16x16x32_bf16 v[94:97], v[146:149], v[196:199], v[94:97]
	v_mfma_f32_16x16x32_bf16 v[82:85], v[154:157], v[196:199], v[82:85]
	v_mfma_f32_16x16x32_bf16 v[78:81], v[146:149], v[212:215], v[78:81]
	v_mfma_f32_16x16x32_bf16 v[66:69], v[154:157], v[212:215], v[66:69]
	v_mfma_f32_16x16x32_bf16 v[126:129], v[150:153], v[166:169], v[126:129]
	v_mfma_f32_16x16x32_bf16 v[114:117], v[158:161], v[166:169], v[114:117]
	v_mfma_f32_16x16x32_bf16 v[110:113], v[150:153], v[174:177], v[110:113]
	v_mfma_f32_16x16x32_bf16 v[98:101], v[158:161], v[174:177], v[98:101]
	v_mfma_f32_16x16x32_bf16 v[94:97], v[150:153], v[208:211], v[94:97]
	v_mfma_f32_16x16x32_bf16 v[82:85], v[158:161], v[208:211], v[82:85]
	v_mfma_f32_16x16x32_bf16 v[78:81], v[150:153], v[216:219], v[78:81]
	v_mfma_f32_16x16x32_bf16 v[66:69], v[158:161], v[216:219], v[66:69]
	s_barrier
	s_add_i32 s34, s73, s17
	s_mov_b32 m0, s34
	ds_read_b128 v[162:165], v207 offset:49152
	ds_read_b128 v[166:169], v207 offset:50176
	ds_read_b128 v[170:173], v207 offset:51200
	ds_read_b128 v[174:177], v207 offset:52224
	ds_read_b128 v[196:199], v207 offset:53248
	ds_read_b128 v[208:211], v207 offset:54272
	ds_read_b128 v[212:215], v207 offset:55296
	ds_read_b128 v[216:219], v207 offset:56320
	global_load_lds_dwordx4 v182, s[98:99]
	s_add_i32 m0, s34, 0x2000
	s_add_u32 s34, s42, 0x100080
	s_addc_u32 s35, s43, 0
	s_add_i32 s42, s74, s17
	global_load_lds_dwordx4 v178, s[98:99]
	s_mov_b32 m0, s42
	s_nop 0
	global_load_lds_dwordx4 v182, s[34:35]
	s_add_i32 m0, s42, 0x2000
	s_nop 0
	global_load_lds_dwordx4 v178, s[34:35]
	s_mov_b32 m0, s64
	s_nop 0
	global_load_lds_dwordx4 v184, s[100:101]
	s_mov_b32 m0, s65
	s_nop 0
	global_load_lds_dwordx4 v180, s[100:101]
	s_waitcnt vmcnt(8)
	s_waitcnt lgkmcnt(0)
	s_barrier
	s_waitcnt lgkmcnt(0)
	v_mfma_f32_16x16x32_bf16 v[58:61], v[130:133], v[162:165], v[58:61]
	v_mfma_f32_16x16x32_bf16 v[54:57], v[138:141], v[162:165], v[54:57]
	v_mfma_f32_16x16x32_bf16 v[42:45], v[130:133], v[170:173], v[42:45]
	v_mfma_f32_16x16x32_bf16 v[38:41], v[138:141], v[170:173], v[38:41]
	v_mfma_f32_16x16x32_bf16 v[26:29], v[130:133], v[196:199], v[26:29]
	v_mfma_f32_16x16x32_bf16 v[22:25], v[138:141], v[196:199], v[22:25]
	v_mfma_f32_16x16x32_bf16 v[10:13], v[130:133], v[212:215], v[10:13]
	v_mfma_f32_16x16x32_bf16 v[6:9], v[138:141], v[212:215], v[6:9]
	v_mfma_f32_16x16x32_bf16 v[58:61], v[134:137], v[166:169], v[58:61]
	v_mfma_f32_16x16x32_bf16 v[54:57], v[142:145], v[166:169], v[54:57]
	v_mfma_f32_16x16x32_bf16 v[42:45], v[134:137], v[174:177], v[42:45]
	v_mfma_f32_16x16x32_bf16 v[38:41], v[142:145], v[174:177], v[38:41]
	v_mfma_f32_16x16x32_bf16 v[26:29], v[134:137], v[208:211], v[26:29]
	v_mfma_f32_16x16x32_bf16 v[22:25], v[142:145], v[208:211], v[22:25]
	v_mfma_f32_16x16x32_bf16 v[10:13], v[134:137], v[216:219], v[10:13]
	v_mfma_f32_16x16x32_bf16 v[6:9], v[142:145], v[216:219], v[6:9]
	v_mfma_f32_16x16x32_bf16 v[62:65], v[146:149], v[162:165], v[62:65]
	v_mfma_f32_16x16x32_bf16 v[50:53], v[154:157], v[162:165], v[50:53]
	v_mfma_f32_16x16x32_bf16 v[46:49], v[146:149], v[170:173], v[46:49]
	v_mfma_f32_16x16x32_bf16 v[34:37], v[154:157], v[170:173], v[34:37]
	v_mfma_f32_16x16x32_bf16 v[30:33], v[146:149], v[196:199], v[30:33]
	v_mfma_f32_16x16x32_bf16 v[18:21], v[154:157], v[196:199], v[18:21]
	v_mfma_f32_16x16x32_bf16 v[14:17], v[146:149], v[212:215], v[14:17]
	v_mfma_f32_16x16x32_bf16 v[2:5], v[154:157], v[212:215], v[2:5]
	v_mfma_f32_16x16x32_bf16 v[62:65], v[150:153], v[166:169], v[62:65]
	v_mfma_f32_16x16x32_bf16 v[50:53], v[158:161], v[166:169], v[50:53]
	v_mfma_f32_16x16x32_bf16 v[46:49], v[150:153], v[174:177], v[46:49]
	v_mfma_f32_16x16x32_bf16 v[34:37], v[158:161], v[174:177], v[34:37]
	v_mfma_f32_16x16x32_bf16 v[30:33], v[150:153], v[208:211], v[30:33]
	v_mfma_f32_16x16x32_bf16 v[18:21], v[158:161], v[208:211], v[18:21]
	v_mfma_f32_16x16x32_bf16 v[14:17], v[150:153], v[216:219], v[14:17]
	v_mfma_f32_16x16x32_bf16 v[2:5], v[158:161], v[216:219], v[2:5]
	s_barrier
	s_add_i32 s53, s53, 2
	s_add_u32 s40, s40, 0x100
	s_addc_u32 s41, s41, 0
	s_add_u32 s45, s45, 0x100
	s_addc_u32 s52, s52, 0
	s_cmp_gt_u32 s53, 61
	s_cbranch_scc0 .LBB0_1127
	s_setprio 0
	s_and_b64 vcc, exec, s[14:15]
	s_cbranch_vccz .LBB0_1130
	s_barrier

; #define PG8_STAGE(bufoff, gbase, voff) do { _Pragma("unroll") for (int _i = 0; _i < 2; ++_i) \
;         __builtin_amdgcn_global_load_lds((const unsigned*)((const char*)(gbase) + (voff)[_i]), (PG8_LAS unsigned*)(lds + (bufoff) + ldsw + _i * 8192), 16, 0, 0); } while (0)
; #define PG8_LDA(dst, b, h) do { _Pragma("unroll") for (int m = 0; m < 4; ++m) _Pragma("unroll") for (int k = 0; k < 2; ++k) dst[m][k] = *(const PG8_LAS bf16x8*)(lds + PG8_SA(b, h) + aoff + m * 2048 + k * 1024); } while (0)
; #define PG8_LDB(dst, b, h) do { _Pragma("unroll") for (int n = 0; n < 2; ++n) _Pragma("unroll") for (int k = 0; k < 2; ++k) dst[n][k] = *(const PG8_LAS bf16x8*)(lds + PG8_SB(b, h) + boff + n * 2048 + k * 1024); } while (0)
; #define PG8_MMA(ai, bj, At, Bt) do { __builtin_amdgcn_s_setprio(1); _Pragma("unroll") for (int m = 0; m < 4; ++m) _Pragma("unroll") for (int n = 0; n < 2; ++n) _Pragma("unroll") for (int k = 0; k < 2; ++k) \
;         acc[ai][bj][m][n] = __builtin_amdgcn_mfma_f32_16x16x32_bf16(Bt[n][k], At[m][k], acc[ai][bj][m][n], 0, 0, 0); __builtin_amdgcn_s_setprio(0); } while (0)
; #define PG8_WAIT_V(n) asm volatile("s_waitcnt vmcnt(" #n ")" ::: "memory")
; #define PG8_WAIT_L(n) asm volatile("s_waitcnt lgkmcnt(" #n ")" ::: "memory")
; #define PG8_BAR __builtin_amdgcn_s_barrier()
; #define PG8_SCHED __builtin_amdgcn_sched_barrier(0)
; template <class Epi, class Sched, bool ALIGN_EPI = false, bool SP2 = false>
; __device__ __forceinline__ void gemm_phase(PG8_LAS unsigned char* lds, const Gemm g, const Sched& S, const Epi& E) {
;     ...
;             PG8_LDB(B0, 0, 0); PG8_LDB(B1, 0, 1); PG8_SCHED; PG8_LDA(At, 0, 0); PG8_STAGE(PG8_SA(1, 1), a1 + hstepA, voffA);
;             PG8_WAIT_V(8); PG8_WAIT_L(0); PG8_BAR; PG8_MMA(0, 0, At, B0); PG8_MMA(0, 1, At, B1); PG8_BAR; PG8_SCHED;
;     ...
; #pragma unroll
;         for (int a = 0; a < 2; ++a)
; #pragma unroll
;             for (int b = 0; b < 2; ++b)
; #pragma unroll
;                 for (int m = 0; m < 4; ++m)
; #pragma unroll
;                     for (int n = 0; n < 2; ++n) acc[a][b][m][n] = (f32x4){0.f, 0.f, 0.f, 0.f};
.LBB0_1205:
	s_add_u32 s62, s36, 0x100
	v_mov_b32_e32 v2, 0
	s_addc_u32 s63, s37, 0
	s_mov_b32 s64, -2
	v_mov_b32_e32 v3, v2
	v_mov_b32_e32 v4, v2
	v_mov_b32_e32 v5, v2
	v_mov_b32_e32 v6, v2
	v_mov_b32_e32 v7, v2
	v_mov_b32_e32 v8, v2
	v_mov_b32_e32 v9, v2
	v_mov_b32_e32 v14, v2
	v_mov_b32_e32 v15, v2
	v_mov_b32_e32 v16, v2
	v_mov_b32_e32 v17, v2
	v_mov_b32_e32 v22, v2
	v_mov_b32_e32 v23, v2
	v_mov_b32_e32 v24, v2
	v_mov_b32_e32 v25, v2
	v_mov_b32_e32 v30, v2
	v_mov_b32_e32 v31, v2
	v_mov_b32_e32 v32, v2
	v_mov_b32_e32 v33, v2
	v_mov_b32_e32 v38, v2
	v_mov_b32_e32 v39, v2
	v_mov_b32_e32 v40, v2
	v_mov_b32_e32 v41, v2
	v_mov_b32_e32 v46, v2
	v_mov_b32_e32 v47, v2
	v_mov_b32_e32 v48, v2
	v_mov_b32_e32 v49, v2
	v_mov_b32_e32 v54, v2
	v_mov_b32_e32 v55, v2
	v_mov_b32_e32 v56, v2
	v_mov_b32_e32 v57, v2
	v_mov_b32_e32 v10, v2
	v_mov_b32_e32 v11, v2
	v_mov_b32_e32 v12, v2
	v_mov_b32_e32 v13, v2
	v_mov_b32_e32 v18, v2
	v_mov_b32_e32 v19, v2
	v_mov_b32_e32 v20, v2
	v_mov_b32_e32 v21, v2
	v_mov_b32_e32 v26, v2
	v_mov_b32_e32 v27, v2
	v_mov_b32_e32 v28, v2
	v_mov_b32_e32 v29, v2
	v_mov_b32_e32 v34, v2
	v_mov_b32_e32 v35, v2
	v_mov_b32_e32 v36, v2
	v_mov_b32_e32 v37, v2
	v_mov_b32_e32 v42, v2
	v_mov_b32_e32 v43, v2
	v_mov_b32_e32 v44, v2
	v_mov_b32_e32 v45, v2
	v_mov_b32_e32 v50, v2
	v_mov_b32_e32 v51, v2
	v_mov_b32_e32 v52, v2
	v_mov_b32_e32 v53, v2
	v_mov_b32_e32 v58, v2
	v_mov_b32_e32 v59, v2
	v_mov_b32_e32 v60, v2
	v_mov_b32_e32 v61, v2
	v_mov_b32_e32 v62, v2
	v_mov_b32_e32 v63, v2
	v_mov_b32_e32 v64, v2
	v_mov_b32_e32 v65, v2
	v_mov_b32_e32 v66, v2
	v_mov_b32_e32 v67, v2
	v_mov_b32_e32 v68, v2
	v_mov_b32_e32 v69, v2
	v_mov_b32_e32 v70, v2
	v_mov_b32_e32 v71, v2
	v_mov_b32_e32 v72, v2
	v_mov_b32_e32 v73, v2
	v_mov_b32_e32 v74, v2
	v_mov_b32_e32 v75, v2
	v_mov_b32_e32 v76, v2
	v_mov_b32_e32 v77, v2
	v_mov_b32_e32 v78, v2
	v_mov_b32_e32 v79, v2
	v_mov_b32_e32 v80, v2
	v_mov_b32_e32 v81, v2
	v_mov_b32_e32 v82, v2
	v_mov_b32_e32 v83, v2
	v_mov_b32_e32 v84, v2
	v_mov_b32_e32 v85, v2
	v_mov_b32_e32 v90, v2
	v_mov_b32_e32 v91, v2
	v_mov_b32_e32 v92, v2
	v_mov_b32_e32 v93, v2
	v_mov_b32_e32 v98, v2
	v_mov_b32_e32 v99, v2
	v_mov_b32_e32 v100, v2
	v_mov_b32_e32 v101, v2
	v_mov_b32_e32 v106, v2
	v_mov_b32_e32 v107, v2
	v_mov_b32_e32 v108, v2
	v_mov_b32_e32 v109, v2
	v_mov_b32_e32 v86, v2
	v_mov_b32_e32 v87, v2
	v_mov_b32_e32 v88, v2
	v_mov_b32_e32 v89, v2
	v_mov_b32_e32 v94, v2
	v_mov_b32_e32 v95, v2
	v_mov_b32_e32 v96, v2
	v_mov_b32_e32 v97, v2
	v_mov_b32_e32 v102, v2
	v_mov_b32_e32 v103, v2
	v_mov_b32_e32 v104, v2
	v_mov_b32_e32 v105, v2
	v_mov_b32_e32 v110, v2
	v_mov_b32_e32 v111, v2
	v_mov_b32_e32 v112, v2
	v_mov_b32_e32 v113, v2
	v_mov_b32_e32 v114, v2
	v_mov_b32_e32 v115, v2
	v_mov_b32_e32 v116, v2
	v_mov_b32_e32 v117, v2
	v_mov_b32_e32 v118, v2
	v_mov_b32_e32 v119, v2
	v_mov_b32_e32 v120, v2
	v_mov_b32_e32 v121, v2
	v_mov_b32_e32 v122, v2
	v_mov_b32_e32 v123, v2
	v_mov_b32_e32 v124, v2
	v_mov_b32_e32 v125, v2
	v_mov_b32_e32 v126, v2
	v_mov_b32_e32 v127, v2
	v_mov_b32_e32 v128, v2
	v_mov_b32_e32 v129, v2
	s_setprio 1
	s_cmp_eq_u64 s[12:13], 0
	s_cbranch_scc1 .Lsp_LBB0_1206
	s_setprio 0
.Lsp_LBB0_1206:
.LBB0_1206:
	ds_read_b128 v[130:133], v166
	ds_read_b128 v[134:137], v166 offset:1024
	ds_read_b128 v[138:141], v166 offset:2048
	ds_read_b128 v[142:145], v166 offset:3072
	ds_read_b128 v[170:173], v167
	ds_read_b128 v[174:177], v167 offset:1024
	ds_read_b128 v[178:181], v167 offset:2048
	ds_read_b128 v[182:185], v167 offset:3072
	s_add_u32 s36, s24, 0x100
	s_addc_u32 s37, s25, 0
	s_cmpk_eq_i32 s64, 0xbc
	s_cselect_b32 s35, s7, s37
	s_cselect_b32 s34, s6, s36
	s_cselect_b32 s39, s23, s63
	s_cselect_b32 s38, s22, s62
	s_add_i32 m0, s27, 0xc000
	ds_read_b128 v[186:189], v168
	ds_read_b128 v[190:193], v168 offset:1024
	ds_read_b128 v[194:197], v168 offset:2048
	ds_read_b128 v[198:201], v168 offset:3072
	ds_read_b128 v[202:205], v168 offset:4096
	ds_read_b128 v[206:209], v168 offset:5120
	ds_read_b128 v[210:213], v168 offset:6144
	ds_read_b128 v[214:217], v168 offset:7168
	global_load_lds_dwordx4 v154, s[24:25]
	s_add_i32 m0, s27, 0xe000
	s_nop 0
	global_load_lds_dwordx4 v156, s[24:25]
	s_waitcnt vmcnt(8)
	s_waitcnt lgkmcnt(0)
	s_barrier
	s_waitcnt lgkmcnt(0)
	v_mfma_f32_16x16x32_bf16 v[126:129], v[130:133], v[186:189], v[126:129]
	v_mfma_f32_16x16x32_bf16 v[122:125], v[138:141], v[186:189], v[122:125]
	v_mfma_f32_16x16x32_bf16 v[118:121], v[130:133], v[194:197], v[118:121]
	v_mfma_f32_16x16x32_bf16 v[114:117], v[138:141], v[194:197], v[114:117]
	v_mfma_f32_16x16x32_bf16 v[110:113], v[130:133], v[202:205], v[110:113]
	v_mfma_f32_16x16x32_bf16 v[102:105], v[138:141], v[202:205], v[102:105]
	v_mfma_f32_16x16x32_bf16 v[94:97], v[130:133], v[210:213], v[94:97]
	v_mfma_f32_16x16x32_bf16 v[86:89], v[138:141], v[210:213], v[86:89]
	v_mfma_f32_16x16x32_bf16 v[126:129], v[134:137], v[190:193], v[126:129]
	v_mfma_f32_16x16x32_bf16 v[122:125], v[142:145], v[190:193], v[122:125]
	v_mfma_f32_16x16x32_bf16 v[118:121], v[134:137], v[198:201], v[118:121]
	v_mfma_f32_16x16x32_bf16 v[114:117], v[142:145], v[198:201], v[114:117]
	v_mfma_f32_16x16x32_bf16 v[110:113], v[134:137], v[206:209], v[110:113]
	v_mfma_f32_16x16x32_bf16 v[102:105], v[142:145], v[206:209], v[102:105]
	v_mfma_f32_16x16x32_bf16 v[94:97], v[134:137], v[214:217], v[94:97]
	v_mfma_f32_16x16x32_bf16 v[86:89], v[142:145], v[214:217], v[86:89]
	v_mfma_f32_16x16x32_bf16 v[106:109], v[170:173], v[186:189], v[106:109]
	v_mfma_f32_16x16x32_bf16 v[98:101], v[178:181], v[186:189], v[98:101]
	v_mfma_f32_16x16x32_bf16 v[90:93], v[170:173], v[194:197], v[90:93]
	v_mfma_f32_16x16x32_bf16 v[82:85], v[178:181], v[194:197], v[82:85]
	v_mfma_f32_16x16x32_bf16 v[78:81], v[170:173], v[202:205], v[78:81]
	v_mfma_f32_16x16x32_bf16 v[74:77], v[178:181], v[202:205], v[74:77]
	v_mfma_f32_16x16x32_bf16 v[70:73], v[170:173], v[210:213], v[70:73]
	v_mfma_f32_16x16x32_bf16 v[66:69], v[178:181], v[210:213], v[66:69]
	v_mfma_f32_16x16x32_bf16 v[106:109], v[174:177], v[190:193], v[106:109]
	v_mfma_f32_16x16x32_bf16 v[98:101], v[182:185], v[190:193], v[98:101]
	v_mfma_f32_16x16x32_bf16 v[90:93], v[174:177], v[198:201], v[90:93]
	v_mfma_f32_16x16x32_bf16 v[82:85], v[182:185], v[198:201], v[82:85]
	v_mfma_f32_16x16x32_bf16 v[78:81], v[174:177], v[206:209], v[78:81]
	v_mfma_f32_16x16x32_bf16 v[74:77], v[182:185], v[206:209], v[74:77]
	v_mfma_f32_16x16x32_bf16 v[70:73], v[174:177], v[214:217], v[70:73]
	v_mfma_f32_16x16x32_bf16 v[66:69], v[182:185], v[214:217], v[66:69]
	s_barrier
; #define PG8_STAGE(bufoff, gbase, voff) do { _Pragma("unroll") for (int _i = 0; _i < 2; ++_i) \
;         __builtin_amdgcn_global_load_lds((const unsigned*)((const char*)(gbase) + (voff)[_i]), (PG8_LAS unsigned*)(lds + (bufoff) + ldsw + _i * 8192), 16, 0, 0); } while (0)
; #define PG8_LDA(dst, b, h) do { _Pragma("unroll") for (int m = 0; m < 4; ++m) _Pragma("unroll") for (int k = 0; k < 2; ++k) dst[m][k] = *(const PG8_LAS bf16x8*)(lds + PG8_SA(b, h) + aoff + m * 2048 + k * 1024); } while (0)
; #define PG8_LDB(dst, b, h) do { _Pragma("unroll") for (int n = 0; n < 2; ++n) _Pragma("unroll") for (int k = 0; k < 2; ++k) dst[n][k] = *(const PG8_LAS bf16x8*)(lds + PG8_SB(b, h) + boff + n * 2048 + k * 1024); } while (0)
; #define PG8_MMA(ai, bj, At, Bt) do { __builtin_amdgcn_s_setprio(1); _Pragma("unroll") for (int m = 0; m < 4; ++m) _Pragma("unroll") for (int n = 0; n < 2; ++n) _Pragma("unroll") for (int k = 0; k < 2; ++k) \
;         acc[ai][bj][m][n] = __builtin_amdgcn_mfma_f32_16x16x32_bf16(Bt[n][k], At[m][k], acc[ai][bj][m][n], 0, 0, 0); __builtin_amdgcn_s_setprio(0); } while (0)
; #define PG8_WAIT_V(n) asm volatile("s_waitcnt vmcnt(" #n ")" ::: "memory")
; #define PG8_WAIT_L(n) asm volatile("s_waitcnt lgkmcnt(" #n ")" ::: "memory")
; #define PG8_BAR __builtin_amdgcn_s_barrier()
; #define PG8_SCHED __builtin_amdgcn_sched_barrier(0)
; template <class Epi, class Sched, bool ALIGN_EPI = false, bool SP2 = false>
; __device__ __forceinline__ void gemm_phase(PG8_LAS unsigned char* lds, const Gemm g, const Sched& S, const Epi& E) {
;     ...
;             PG8_LDA(At, 0, 1); PG8_STAGE(PG8_SB(0, 0), b2, voffB); PG8_STAGE(PG8_SB(0, 1), b2 + hstepB, voffB); PG8_STAGE(PG8_SA(0, 0), a2, voffA);
;             PG8_WAIT_V(8); PG8_WAIT_L(0); PG8_BAR; PG8_MMA(1, 0, At, B0); PG8_MMA(1, 1, At, B1); PG8_BAR; PG8_SCHED;
;             PG8_LDB(B0, 1, 0); PG8_LDB(B1, 1, 1); PG8_SCHED; PG8_LDA(At, 1, 0); PG8_STAGE(PG8_SA(0, 1), a2 + hstepA, voffA);
	s_add_i32 s24, s48, s26
	s_add_u32 s98, s38, 0x80
	s_addc_u32 s99, s39, 0
	s_add_u32 s100, s34, 0x80
	s_addc_u32 s101, s35, 0
	s_mov_b32 m0, s24
	ds_read_b128 v[186:189], v168 offset:16384
	ds_read_b128 v[190:193], v168 offset:17408
	ds_read_b128 v[194:197], v168 offset:18432
	ds_read_b128 v[198:201], v168 offset:19456
	ds_read_b128 v[202:205], v168 offset:20480
	ds_read_b128 v[206:209], v168 offset:21504
	ds_read_b128 v[210:213], v168 offset:22528
	ds_read_b128 v[214:217], v168 offset:23552
	global_load_lds_dwordx4 v150, s[38:39]
	s_add_i32 m0, s24, 0x2000
	s_add_u32 s24, s38, 0x300000
	s_addc_u32 s25, s39, 0
	s_add_i32 s65, s49, s26
	global_load_lds_dwordx4 v146, s[38:39]
	s_mov_b32 m0, s65
	s_nop 0
	global_load_lds_dwordx4 v150, s[24:25]
	s_add_i32 m0, s65, 0x2000
	s_nop 0
	global_load_lds_dwordx4 v146, s[24:25]
	s_mov_b32 m0, s27
	s_nop 0
	global_load_lds_dwordx4 v152, s[34:35]
	s_mov_b32 m0, s40
	s_nop 0
	global_load_lds_dwordx4 v148, s[34:35]
	s_waitcnt vmcnt(8)
	s_waitcnt lgkmcnt(0)
	s_barrier
	s_waitcnt lgkmcnt(0)
	v_mfma_f32_16x16x32_bf16 v[62:65], v[130:133], v[186:189], v[62:65]
	v_mfma_f32_16x16x32_bf16 v[58:61], v[138:141], v[186:189], v[58:61]
	v_mfma_f32_16x16x32_bf16 v[50:53], v[130:133], v[194:197], v[50:53]
	v_mfma_f32_16x16x32_bf16 v[42:45], v[138:141], v[194:197], v[42:45]
	v_mfma_f32_16x16x32_bf16 v[34:37], v[130:133], v[202:205], v[34:37]
	v_mfma_f32_16x16x32_bf16 v[26:29], v[138:141], v[202:205], v[26:29]
	v_mfma_f32_16x16x32_bf16 v[18:21], v[130:133], v[210:213], v[18:21]
	v_mfma_f32_16x16x32_bf16 v[10:13], v[138:141], v[210:213], v[10:13]
	v_mfma_f32_16x16x32_bf16 v[62:65], v[134:137], v[190:193], v[62:65]
	v_mfma_f32_16x16x32_bf16 v[58:61], v[142:145], v[190:193], v[58:61]
	v_mfma_f32_16x16x32_bf16 v[50:53], v[134:137], v[198:201], v[50:53]
	v_mfma_f32_16x16x32_bf16 v[42:45], v[142:145], v[198:201], v[42:45]
	v_mfma_f32_16x16x32_bf16 v[34:37], v[134:137], v[206:209], v[34:37]
	v_mfma_f32_16x16x32_bf16 v[26:29], v[142:145], v[206:209], v[26:29]
	v_mfma_f32_16x16x32_bf16 v[18:21], v[134:137], v[214:217], v[18:21]
	v_mfma_f32_16x16x32_bf16 v[10:13], v[142:145], v[214:217], v[10:13]
	v_mfma_f32_16x16x32_bf16 v[54:57], v[170:173], v[186:189], v[54:57]
	v_mfma_f32_16x16x32_bf16 v[46:49], v[178:181], v[186:189], v[46:49]
	v_mfma_f32_16x16x32_bf16 v[38:41], v[170:173], v[194:197], v[38:41]
	v_mfma_f32_16x16x32_bf16 v[30:33], v[178:181], v[194:197], v[30:33]
	v_mfma_f32_16x16x32_bf16 v[22:25], v[170:173], v[202:205], v[22:25]
	v_mfma_f32_16x16x32_bf16 v[14:17], v[178:181], v[202:205], v[14:17]
	v_mfma_f32_16x16x32_bf16 v[6:9], v[170:173], v[210:213], v[6:9]
	v_mfma_f32_16x16x32_bf16 v[2:5], v[178:181], v[210:213], v[2:5]
	v_mfma_f32_16x16x32_bf16 v[54:57], v[174:177], v[190:193], v[54:57]
	v_mfma_f32_16x16x32_bf16 v[46:49], v[182:185], v[190:193], v[46:49]
	v_mfma_f32_16x16x32_bf16 v[38:41], v[174:177], v[198:201], v[38:41]
	v_mfma_f32_16x16x32_bf16 v[30:33], v[182:185], v[198:201], v[30:33]
	v_mfma_f32_16x16x32_bf16 v[22:25], v[174:177], v[206:209], v[22:25]
	v_mfma_f32_16x16x32_bf16 v[14:17], v[182:185], v[206:209], v[14:17]
	v_mfma_f32_16x16x32_bf16 v[6:9], v[174:177], v[214:217], v[6:9]
	v_mfma_f32_16x16x32_bf16 v[2:5], v[182:185], v[214:217], v[2:5]
	s_barrier
	s_add_i32 s65, 0, 0x18000
	s_add_i32 s66, 0, 0x1c000
	v_add_u32_e32 v142, s65, v164
	v_add_u32_e32 v169, s66, v164
	ds_read_b128 v[130:133], v142
	ds_read_b128 v[134:137], v142 offset:1024
	ds_read_b128 v[138:141], v142 offset:2048
	ds_read_b128 v[142:145], v142 offset:3072
	ds_read_b128 v[170:173], v169
	ds_read_b128 v[174:177], v169 offset:1024
	ds_read_b128 v[178:181], v169 offset:2048
	ds_read_b128 v[182:185], v169 offset:3072
	s_add_u32 s24, s34, 0x300000
	s_addc_u32 s25, s35, 0
	s_mov_b32 m0, s41
	ds_read_b128 v[186:189], v168 offset:32768
	ds_read_b128 v[190:193], v168 offset:33792
	ds_read_b128 v[194:197], v168 offset:34816
	ds_read_b128 v[198:201], v168 offset:35840
	ds_read_b128 v[202:205], v168 offset:36864
	ds_read_b128 v[206:209], v168 offset:37888
	ds_read_b128 v[210:213], v168 offset:38912
	ds_read_b128 v[214:217], v168 offset:39936
	global_load_lds_dwordx4 v152, s[24:25]
	s_mov_b32 m0, s42
	s_nop 0
	global_load_lds_dwordx4 v148, s[24:25]
	s_waitcnt vmcnt(8)
	s_waitcnt lgkmcnt(0)
	s_barrier
; #define PG8_STAGE(bufoff, gbase, voff) do { _Pragma("unroll") for (int _i = 0; _i < 2; ++_i) \
;         __builtin_amdgcn_global_load_lds((const unsigned*)((const char*)(gbase) + (voff)[_i]), (PG8_LAS unsigned*)(lds + (bufoff) + ldsw + _i * 8192), 16, 0, 0); } while (0)
; #define PG8_LDA(dst, b, h) do { _Pragma("unroll") for (int m = 0; m < 4; ++m) _Pragma("unroll") for (int k = 0; k < 2; ++k) dst[m][k] = *(const PG8_LAS bf16x8*)(lds + PG8_SA(b, h) + aoff + m * 2048 + k * 1024); } while (0)
; #define PG8_LDB(dst, b, h) do { _Pragma("unroll") for (int n = 0; n < 2; ++n) _Pragma("unroll") for (int k = 0; k < 2; ++k) dst[n][k] = *(const PG8_LAS bf16x8*)(lds + PG8_SB(b, h) + boff + n * 2048 + k * 1024); } while (0)
; #define PG8_MMA(ai, bj, At, Bt) do { __builtin_amdgcn_s_setprio(1); _Pragma("unroll") for (int m = 0; m < 4; ++m) _Pragma("unroll") for (int n = 0; n < 2; ++n) _Pragma("unroll") for (int k = 0; k < 2; ++k) \
;         acc[ai][bj][m][n] = __builtin_amdgcn_mfma_f32_16x16x32_bf16(Bt[n][k], At[m][k], acc[ai][bj][m][n], 0, 0, 0); __builtin_amdgcn_s_setprio(0); } while (0)
; #define PG8_WAIT_V(n) asm volatile("s_waitcnt vmcnt(" #n ")" ::: "memory")
; #define PG8_WAIT_L(n) asm volatile("s_waitcnt lgkmcnt(" #n ")" ::: "memory")
; #define PG8_BAR __builtin_amdgcn_s_barrier()
; #define PG8_SCHED __builtin_amdgcn_sched_barrier(0)
; template <class Epi, class Sched, bool ALIGN_EPI = false, bool SP2 = false>
; __device__ __forceinline__ void gemm_phase(PG8_LAS unsigned char* lds, const Gemm g, const Sched& S, const Epi& E) {
;     ...
;         for (int t = 0; t < nt; t += 2) {
;     ...
;             PG8_LDB(B0, 1, 0); PG8_LDB(B1, 1, 1); PG8_SCHED; PG8_LDA(At, 1, 0); PG8_STAGE(PG8_SA(0, 1), a2 + hstepA, voffA);
;             PG8_WAIT_V(8); PG8_WAIT_L(0); PG8_BAR; PG8_MMA(0, 0, At, B0); PG8_MMA(0, 1, At, B1); PG8_BAR; PG8_SCHED;
;             PG8_LDA(At, 1, 1); PG8_STAGE(PG8_SB(1, 0), b3, voffB); PG8_STAGE(PG8_SB(1, 1), b3 + hstepB, voffB); PG8_STAGE(PG8_SA(1, 0), a3, voffA);
;             PG8_WAIT_V(8); PG8_WAIT_L(0); PG8_BAR; PG8_MMA(1, 0, At, B0); PG8_MMA(1, 1, At, B1); PG8_BAR; PG8_SCHED;
	s_waitcnt lgkmcnt(0)
	v_mfma_f32_16x16x32_bf16 v[126:129], v[130:133], v[186:189], v[126:129]
	v_mfma_f32_16x16x32_bf16 v[122:125], v[138:141], v[186:189], v[122:125]
	v_mfma_f32_16x16x32_bf16 v[118:121], v[130:133], v[194:197], v[118:121]
	v_mfma_f32_16x16x32_bf16 v[114:117], v[138:141], v[194:197], v[114:117]
	v_mfma_f32_16x16x32_bf16 v[110:113], v[130:133], v[202:205], v[110:113]
	v_mfma_f32_16x16x32_bf16 v[102:105], v[138:141], v[202:205], v[102:105]
	v_mfma_f32_16x16x32_bf16 v[94:97], v[130:133], v[210:213], v[94:97]
	v_mfma_f32_16x16x32_bf16 v[86:89], v[138:141], v[210:213], v[86:89]
	v_mfma_f32_16x16x32_bf16 v[126:129], v[134:137], v[190:193], v[126:129]
	v_mfma_f32_16x16x32_bf16 v[122:125], v[142:145], v[190:193], v[122:125]
	v_mfma_f32_16x16x32_bf16 v[118:121], v[134:137], v[198:201], v[118:121]
	v_mfma_f32_16x16x32_bf16 v[114:117], v[142:145], v[198:201], v[114:117]
	v_mfma_f32_16x16x32_bf16 v[110:113], v[134:137], v[206:209], v[110:113]
	v_mfma_f32_16x16x32_bf16 v[102:105], v[142:145], v[206:209], v[102:105]
	v_mfma_f32_16x16x32_bf16 v[94:97], v[134:137], v[214:217], v[94:97]
	v_mfma_f32_16x16x32_bf16 v[86:89], v[142:145], v[214:217], v[86:89]
	v_mfma_f32_16x16x32_bf16 v[106:109], v[170:173], v[186:189], v[106:109]
	v_mfma_f32_16x16x32_bf16 v[98:101], v[178:181], v[186:189], v[98:101]
	v_mfma_f32_16x16x32_bf16 v[90:93], v[170:173], v[194:197], v[90:93]
	v_mfma_f32_16x16x32_bf16 v[82:85], v[178:181], v[194:197], v[82:85]
	v_mfma_f32_16x16x32_bf16 v[78:81], v[170:173], v[202:205], v[78:81]
	v_mfma_f32_16x16x32_bf16 v[74:77], v[178:181], v[202:205], v[74:77]
	v_mfma_f32_16x16x32_bf16 v[70:73], v[170:173], v[210:213], v[70:73]
	v_mfma_f32_16x16x32_bf16 v[66:69], v[178:181], v[210:213], v[66:69]
	v_mfma_f32_16x16x32_bf16 v[106:109], v[174:177], v[190:193], v[106:109]
	v_mfma_f32_16x16x32_bf16 v[98:101], v[182:185], v[190:193], v[98:101]
	v_mfma_f32_16x16x32_bf16 v[90:93], v[174:177], v[198:201], v[90:93]
	v_mfma_f32_16x16x32_bf16 v[82:85], v[182:185], v[198:201], v[82:85]
	v_mfma_f32_16x16x32_bf16 v[78:81], v[174:177], v[206:209], v[78:81]
	v_mfma_f32_16x16x32_bf16 v[74:77], v[182:185], v[206:209], v[74:77]
	v_mfma_f32_16x16x32_bf16 v[70:73], v[174:177], v[214:217], v[70:73]
	v_mfma_f32_16x16x32_bf16 v[66:69], v[182:185], v[214:217], v[66:69]
	s_barrier
	s_add_i32 s24, s65, s26
	s_mov_b32 m0, s24
	ds_read_b128 v[186:189], v168 offset:49152
	ds_read_b128 v[190:193], v168 offset:50176
	ds_read_b128 v[194:197], v168 offset:51200
	ds_read_b128 v[198:201], v168 offset:52224
	ds_read_b128 v[202:205], v168 offset:53248
	ds_read_b128 v[206:209], v168 offset:54272
	ds_read_b128 v[210:213], v168 offset:55296
	ds_read_b128 v[214:217], v168 offset:56320
	global_load_lds_dwordx4 v150, s[98:99]
	s_add_i32 m0, s24, 0x2000
	s_add_u32 s24, s38, 0x300080
	s_addc_u32 s25, s39, 0
	s_add_i32 s34, s66, s26
	global_load_lds_dwordx4 v146, s[98:99]
	s_mov_b32 m0, s34
	s_nop 0
	global_load_lds_dwordx4 v150, s[24:25]
	s_add_i32 m0, s34, 0x2000
	s_nop 0
	global_load_lds_dwordx4 v146, s[24:25]
	s_mov_b32 m0, s46
	s_nop 0
	global_load_lds_dwordx4 v152, s[100:101]
	s_mov_b32 m0, s47
	s_nop 0
	global_load_lds_dwordx4 v148, s[100:101]
	s_waitcnt vmcnt(8)
	s_waitcnt lgkmcnt(0)
	s_barrier
	s_waitcnt lgkmcnt(0)
	v_mfma_f32_16x16x32_bf16 v[62:65], v[130:133], v[186:189], v[62:65]
	v_mfma_f32_16x16x32_bf16 v[58:61], v[138:141], v[186:189], v[58:61]
	v_mfma_f32_16x16x32_bf16 v[50:53], v[130:133], v[194:197], v[50:53]
	v_mfma_f32_16x16x32_bf16 v[42:45], v[138:141], v[194:197], v[42:45]
	v_mfma_f32_16x16x32_bf16 v[34:37], v[130:133], v[202:205], v[34:37]
	v_mfma_f32_16x16x32_bf16 v[26:29], v[138:141], v[202:205], v[26:29]
	v_mfma_f32_16x16x32_bf16 v[18:21], v[130:133], v[210:213], v[18:21]
	v_mfma_f32_16x16x32_bf16 v[10:13], v[138:141], v[210:213], v[10:13]
	v_mfma_f32_16x16x32_bf16 v[62:65], v[134:137], v[190:193], v[62:65]
	v_mfma_f32_16x16x32_bf16 v[58:61], v[142:145], v[190:193], v[58:61]
	v_mfma_f32_16x16x32_bf16 v[50:53], v[134:137], v[198:201], v[50:53]
	v_mfma_f32_16x16x32_bf16 v[42:45], v[142:145], v[198:201], v[42:45]
	v_mfma_f32_16x16x32_bf16 v[34:37], v[134:137], v[206:209], v[34:37]
	v_mfma_f32_16x16x32_bf16 v[26:29], v[142:145], v[206:209], v[26:29]
	v_mfma_f32_16x16x32_bf16 v[18:21], v[134:137], v[214:217], v[18:21]
	v_mfma_f32_16x16x32_bf16 v[10:13], v[142:145], v[214:217], v[10:13]
	v_mfma_f32_16x16x32_bf16 v[54:57], v[170:173], v[186:189], v[54:57]
	v_mfma_f32_16x16x32_bf16 v[46:49], v[178:181], v[186:189], v[46:49]
	v_mfma_f32_16x16x32_bf16 v[38:41], v[170:173], v[194:197], v[38:41]
	v_mfma_f32_16x16x32_bf16 v[30:33], v[178:181], v[194:197], v[30:33]
	v_mfma_f32_16x16x32_bf16 v[22:25], v[170:173], v[202:205], v[22:25]
	v_mfma_f32_16x16x32_bf16 v[14:17], v[178:181], v[202:205], v[14:17]
	v_mfma_f32_16x16x32_bf16 v[6:9], v[170:173], v[210:213], v[6:9]
	v_mfma_f32_16x16x32_bf16 v[2:5], v[178:181], v[210:213], v[2:5]
	v_mfma_f32_16x16x32_bf16 v[54:57], v[174:177], v[190:193], v[54:57]
	v_mfma_f32_16x16x32_bf16 v[46:49], v[182:185], v[190:193], v[46:49]
	v_mfma_f32_16x16x32_bf16 v[38:41], v[174:177], v[198:201], v[38:41]
	v_mfma_f32_16x16x32_bf16 v[30:33], v[182:185], v[198:201], v[30:33]
	v_mfma_f32_16x16x32_bf16 v[22:25], v[174:177], v[206:209], v[22:25]
	v_mfma_f32_16x16x32_bf16 v[14:17], v[182:185], v[206:209], v[14:17]
	v_mfma_f32_16x16x32_bf16 v[6:9], v[174:177], v[214:217], v[6:9]
	v_mfma_f32_16x16x32_bf16 v[2:5], v[182:185], v[214:217], v[2:5]
	s_barrier
	s_add_i32 s64, s64, 2
	s_add_u32 s62, s62, 0x100
	s_addc_u32 s63, s63, 0
	s_cmpk_gt_u32 s64, 0xbd
	s_mov_b64 s[24:25], s[36:37]
	s_cbranch_scc0 .LBB0_1206
	s_setprio 0
	s_and_b64 vcc, exec, s[12:13]
	s_cbranch_vccz .LBB0_1209
	s_barrier
